# no GEMM-loop priority toggles, plus the m0-to-DMA wait states filled by the load segment's own ds_reads instead of s_nop
# baseline (speedup 1.0000x reference)
.LBB0_163:
	ds_read_b128 v[152:155], v149
	ds_read_b128 v[156:159], v149 offset:1024
	ds_read_b128 v[160:163], v149 offset:2048
	ds_read_b128 v[164:167], v149 offset:3072
	ds_read_b128 v[168:171], v150
	ds_read_b128 v[172:175], v150 offset:1024
	ds_read_b128 v[176:179], v150 offset:2048
	ds_read_b128 v[180:183], v150 offset:3072
	s_add_u32 s24, s22, 0xfff80080
	s_addc_u32 s25, s23, -1
	s_cmp_eq_u32 s58, 28
	s_cselect_b32 s27, s15, s25
	s_cselect_b32 s26, s54, s24
	s_cselect_b32 s25, s13, s57
	s_cselect_b32 s24, s55, s56
	s_add_u32 s98, s24, s6
	s_addc_u32 s99, s25, s7
	s_add_u32 s100, s26, s6
	s_addc_u32 s101, s27, s7
	s_add_i32 m0, s21, 0xc000
	ds_read_b128 v[184:187], v151
	ds_read_b128 v[188:191], v151 offset:1024
	ds_read_b128 v[192:195], v151 offset:2048
	ds_read_b128 v[196:199], v151 offset:3072
	ds_read_b128 v[200:203], v151 offset:4096
	ds_read_b128 v[204:207], v151 offset:5120
	ds_read_b128 v[208:211], v151 offset:6144
	global_load_lds_dwordx4 v136, s[22:23]
	s_add_i32 m0, s21, 0xe000
	ds_read_b128 v[212:215], v151 offset:7168
	global_load_lds_dwordx4 v138, s[22:23]
	s_waitcnt vmcnt(8)
	s_waitcnt lgkmcnt(0)
	s_barrier
	s_waitcnt lgkmcnt(0)
	v_mfma_f32_16x16x32_bf16 v[124:127], v[152:155], v[184:187], v[124:127]
	v_mfma_f32_16x16x32_bf16 v[120:123], v[160:163], v[184:187], v[120:123]
	v_mfma_f32_16x16x32_bf16 v[116:119], v[152:155], v[192:195], v[116:119]
	v_mfma_f32_16x16x32_bf16 v[108:111], v[160:163], v[192:195], v[108:111]
	v_mfma_f32_16x16x32_bf16 v[100:103], v[152:155], v[200:203], v[100:103]
	v_mfma_f32_16x16x32_bf16 v[92:95], v[160:163], v[200:203], v[92:95]
	v_mfma_f32_16x16x32_bf16 v[84:87], v[152:155], v[208:211], v[84:87]
	v_mfma_f32_16x16x32_bf16 v[76:79], v[160:163], v[208:211], v[76:79]
	v_mfma_f32_16x16x32_bf16 v[124:127], v[156:159], v[188:191], v[124:127]
	v_mfma_f32_16x16x32_bf16 v[120:123], v[164:167], v[188:191], v[120:123]
	v_mfma_f32_16x16x32_bf16 v[116:119], v[156:159], v[196:199], v[116:119]
	v_mfma_f32_16x16x32_bf16 v[108:111], v[164:167], v[196:199], v[108:111]
	v_mfma_f32_16x16x32_bf16 v[100:103], v[156:159], v[204:207], v[100:103]
	v_mfma_f32_16x16x32_bf16 v[92:95], v[164:167], v[204:207], v[92:95]
	v_mfma_f32_16x16x32_bf16 v[84:87], v[156:159], v[212:215], v[84:87]
	v_mfma_f32_16x16x32_bf16 v[76:79], v[164:167], v[212:215], v[76:79]
	v_mfma_f32_16x16x32_bf16 v[112:115], v[168:171], v[184:187], v[112:115]
	v_mfma_f32_16x16x32_bf16 v[104:107], v[176:179], v[184:187], v[104:107]
	v_mfma_f32_16x16x32_bf16 v[96:99], v[168:171], v[192:195], v[96:99]
	v_mfma_f32_16x16x32_bf16 v[88:91], v[176:179], v[192:195], v[88:91]
	v_mfma_f32_16x16x32_bf16 v[80:83], v[168:171], v[200:203], v[80:83]
	v_mfma_f32_16x16x32_bf16 v[72:75], v[176:179], v[200:203], v[72:75]
	v_mfma_f32_16x16x32_bf16 v[68:71], v[168:171], v[208:211], v[68:71]
	v_mfma_f32_16x16x32_bf16 v[64:67], v[176:179], v[208:211], v[64:67]
	v_mfma_f32_16x16x32_bf16 v[112:115], v[172:175], v[188:191], v[112:115]
	v_mfma_f32_16x16x32_bf16 v[104:107], v[180:183], v[188:191], v[104:107]
	v_mfma_f32_16x16x32_bf16 v[96:99], v[172:175], v[196:199], v[96:99]
	v_mfma_f32_16x16x32_bf16 v[88:91], v[180:183], v[196:199], v[88:91]
	v_mfma_f32_16x16x32_bf16 v[80:83], v[172:175], v[204:207], v[80:83]
	v_mfma_f32_16x16x32_bf16 v[72:75], v[180:183], v[204:207], v[72:75]
	v_mfma_f32_16x16x32_bf16 v[68:71], v[172:175], v[212:215], v[68:71]
	v_mfma_f32_16x16x32_bf16 v[64:67], v[180:183], v[212:215], v[64:67]
	s_barrier
	s_add_i32 s59, s43, s28
	s_mov_b32 m0, s59
	ds_read_b128 v[184:187], v151 offset:16384
	ds_read_b128 v[188:191], v151 offset:17408
	ds_read_b128 v[192:195], v151 offset:18432
	ds_read_b128 v[196:199], v151 offset:19456
	global_load_lds_dwordx4 v130, s[24:25]
	s_add_i32 m0, s59, 0x2000
	s_add_u32 s62, s24, 0x200000
	s_addc_u32 s63, s25, 0
	s_add_i32 s59, s48, s28
	global_load_lds_dwordx4 v134, s[24:25]
	s_mov_b32 m0, s59
	ds_read_b128 v[212:215], v151 offset:23552
	global_load_lds_dwordx4 v130, s[62:63]
	s_add_i32 m0, s59, 0x2000
	ds_read_b128 v[208:211], v151 offset:22528
	global_load_lds_dwordx4 v134, s[62:63]
	s_mov_b32 m0, s21
	ds_read_b128 v[204:207], v151 offset:21504
	global_load_lds_dwordx4 v128, s[26:27]
	s_mov_b32 m0, s31
	ds_read_b128 v[200:203], v151 offset:20480
	global_load_lds_dwordx4 v132, s[26:27]
	s_waitcnt vmcnt(8)
	s_waitcnt lgkmcnt(0)
	s_barrier
	s_waitcnt lgkmcnt(0)
	v_mfma_f32_16x16x32_bf16 v[60:63], v[152:155], v[184:187], v[60:63]
	v_mfma_f32_16x16x32_bf16 v[56:59], v[160:163], v[184:187], v[56:59]
	v_mfma_f32_16x16x32_bf16 v[52:55], v[152:155], v[192:195], v[52:55]
	v_mfma_f32_16x16x32_bf16 v[44:47], v[160:163], v[192:195], v[44:47]
	v_mfma_f32_16x16x32_bf16 v[36:39], v[152:155], v[200:203], v[36:39]
	v_mfma_f32_16x16x32_bf16 v[28:31], v[160:163], v[200:203], v[28:31]
	v_mfma_f32_16x16x32_bf16 v[20:23], v[152:155], v[208:211], v[20:23]
	v_mfma_f32_16x16x32_bf16 v[12:15], v[160:163], v[208:211], v[12:15]
	v_mfma_f32_16x16x32_bf16 v[60:63], v[156:159], v[188:191], v[60:63]
	v_mfma_f32_16x16x32_bf16 v[56:59], v[164:167], v[188:191], v[56:59]
	v_mfma_f32_16x16x32_bf16 v[52:55], v[156:159], v[196:199], v[52:55]
	v_mfma_f32_16x16x32_bf16 v[44:47], v[164:167], v[196:199], v[44:47]
	v_mfma_f32_16x16x32_bf16 v[36:39], v[156:159], v[204:207], v[36:39]
	v_mfma_f32_16x16x32_bf16 v[28:31], v[164:167], v[204:207], v[28:31]
	v_mfma_f32_16x16x32_bf16 v[20:23], v[156:159], v[212:215], v[20:23]
	v_mfma_f32_16x16x32_bf16 v[12:15], v[164:167], v[212:215], v[12:15]
	v_mfma_f32_16x16x32_bf16 v[48:51], v[168:171], v[184:187], v[48:51]
	v_mfma_f32_16x16x32_bf16 v[40:43], v[176:179], v[184:187], v[40:43]
	v_mfma_f32_16x16x32_bf16 v[32:35], v[168:171], v[192:195], v[32:35]
	v_mfma_f32_16x16x32_bf16 v[24:27], v[176:179], v[192:195], v[24:27]
	v_mfma_f32_16x16x32_bf16 v[16:19], v[168:171], v[200:203], v[16:19]
	v_mfma_f32_16x16x32_bf16 v[8:11], v[176:179], v[200:203], v[8:11]
	v_mfma_f32_16x16x32_bf16 v[4:7], v[168:171], v[208:211], v[4:7]
	v_mfma_f32_16x16x32_bf16 v[0:3], v[176:179], v[208:211], v[0:3]
	v_mfma_f32_16x16x32_bf16 v[48:51], v[172:175], v[188:191], v[48:51]
	v_mfma_f32_16x16x32_bf16 v[40:43], v[180:183], v[188:191], v[40:43]
	v_mfma_f32_16x16x32_bf16 v[32:35], v[172:175], v[196:199], v[32:35]
	v_mfma_f32_16x16x32_bf16 v[24:27], v[180:183], v[196:199], v[24:27]
	v_mfma_f32_16x16x32_bf16 v[16:19], v[172:175], v[204:207], v[16:19]
	v_mfma_f32_16x16x32_bf16 v[8:11], v[180:183], v[204:207], v[8:11]
	v_mfma_f32_16x16x32_bf16 v[4:7], v[172:175], v[212:215], v[4:7]
	v_mfma_f32_16x16x32_bf16 v[0:3], v[180:183], v[212:215], v[0:3]
	s_barrier
	s_add_i32 s59, 0, 0x18000
	s_add_i32 s62, 0, 0x1c000
	v_add_u32_e32 v164, s59, v146
	v_add_u32_e32 v180, s62, v146
	ds_read_b128 v[152:155], v164
	ds_read_b128 v[156:159], v164 offset:1024
	ds_read_b128 v[160:163], v164 offset:2048
	ds_read_b128 v[164:167], v164 offset:3072
	ds_read_b128 v[168:171], v180
	ds_read_b128 v[172:175], v180 offset:1024
	ds_read_b128 v[176:179], v180 offset:2048
	ds_read_b128 v[180:183], v180 offset:3072
	s_add_u32 s26, s26, 0x80000
	s_addc_u32 s27, s27, 0
	s_mov_b32 m0, s34
	ds_read_b128 v[184:187], v151 offset:32768
	ds_read_b128 v[188:191], v151 offset:33792
	ds_read_b128 v[192:195], v151 offset:34816
	ds_read_b128 v[196:199], v151 offset:35840
	ds_read_b128 v[200:203], v151 offset:36864
	ds_read_b128 v[204:207], v151 offset:37888
	ds_read_b128 v[208:211], v151 offset:38912
	global_load_lds_dwordx4 v128, s[26:27]
	s_mov_b32 m0, s35
	ds_read_b128 v[212:215], v151 offset:39936
	global_load_lds_dwordx4 v132, s[26:27]
	s_waitcnt vmcnt(8)
	s_waitcnt lgkmcnt(0)
	s_barrier
	s_waitcnt lgkmcnt(0)
	v_mfma_f32_16x16x32_bf16 v[124:127], v[152:155], v[184:187], v[124:127]
	v_mfma_f32_16x16x32_bf16 v[120:123], v[160:163], v[184:187], v[120:123]
	v_mfma_f32_16x16x32_bf16 v[116:119], v[152:155], v[192:195], v[116:119]
	v_mfma_f32_16x16x32_bf16 v[108:111], v[160:163], v[192:195], v[108:111]
	v_mfma_f32_16x16x32_bf16 v[100:103], v[152:155], v[200:203], v[100:103]
	v_mfma_f32_16x16x32_bf16 v[92:95], v[160:163], v[200:203], v[92:95]
	v_mfma_f32_16x16x32_bf16 v[84:87], v[152:155], v[208:211], v[84:87]
	v_mfma_f32_16x16x32_bf16 v[76:79], v[160:163], v[208:211], v[76:79]
	v_mfma_f32_16x16x32_bf16 v[124:127], v[156:159], v[188:191], v[124:127]
	v_mfma_f32_16x16x32_bf16 v[120:123], v[164:167], v[188:191], v[120:123]
	v_mfma_f32_16x16x32_bf16 v[116:119], v[156:159], v[196:199], v[116:119]
	v_mfma_f32_16x16x32_bf16 v[108:111], v[164:167], v[196:199], v[108:111]
	v_mfma_f32_16x16x32_bf16 v[100:103], v[156:159], v[204:207], v[100:103]
	v_mfma_f32_16x16x32_bf16 v[92:95], v[164:167], v[204:207], v[92:95]
	v_mfma_f32_16x16x32_bf16 v[84:87], v[156:159], v[212:215], v[84:87]
	v_mfma_f32_16x16x32_bf16 v[76:79], v[164:167], v[212:215], v[76:79]
	v_mfma_f32_16x16x32_bf16 v[112:115], v[168:171], v[184:187], v[112:115]
	v_mfma_f32_16x16x32_bf16 v[104:107], v[176:179], v[184:187], v[104:107]
	v_mfma_f32_16x16x32_bf16 v[96:99], v[168:171], v[192:195], v[96:99]
	v_mfma_f32_16x16x32_bf16 v[88:91], v[176:179], v[192:195], v[88:91]
	v_mfma_f32_16x16x32_bf16 v[80:83], v[168:171], v[200:203], v[80:83]
	v_mfma_f32_16x16x32_bf16 v[72:75], v[176:179], v[200:203], v[72:75]
	v_mfma_f32_16x16x32_bf16 v[68:71], v[168:171], v[208:211], v[68:71]
	v_mfma_f32_16x16x32_bf16 v[64:67], v[176:179], v[208:211], v[64:67]
	v_mfma_f32_16x16x32_bf16 v[112:115], v[172:175], v[188:191], v[112:115]
	v_mfma_f32_16x16x32_bf16 v[104:107], v[180:183], v[188:191], v[104:107]
	v_mfma_f32_16x16x32_bf16 v[96:99], v[172:175], v[196:199], v[96:99]
	v_mfma_f32_16x16x32_bf16 v[88:91], v[180:183], v[196:199], v[88:91]
	v_mfma_f32_16x16x32_bf16 v[80:83], v[172:175], v[204:207], v[80:83]
	v_mfma_f32_16x16x32_bf16 v[72:75], v[180:183], v[204:207], v[72:75]
	v_mfma_f32_16x16x32_bf16 v[68:71], v[172:175], v[212:215], v[68:71]
	v_mfma_f32_16x16x32_bf16 v[64:67], v[180:183], v[212:215], v[64:67]
	s_barrier
	s_add_i32 s26, s59, s28
	s_mov_b32 m0, s26
	ds_read_b128 v[184:187], v151 offset:49152
	ds_read_b128 v[188:191], v151 offset:50176
	ds_read_b128 v[192:195], v151 offset:51200
	ds_read_b128 v[196:199], v151 offset:52224
	global_load_lds_dwordx4 v130, s[98:99]
	s_add_i32 m0, s26, 0x2000
	s_add_u32 s24, s24, 0x200080
	s_addc_u32 s25, s25, 0
	s_add_i32 s26, s62, s28
	global_load_lds_dwordx4 v134, s[98:99]
	s_mov_b32 m0, s26
	ds_read_b128 v[212:215], v151 offset:56320
	global_load_lds_dwordx4 v130, s[24:25]
	s_add_i32 m0, s26, 0x2000
	ds_read_b128 v[208:211], v151 offset:55296
	global_load_lds_dwordx4 v134, s[24:25]
	s_mov_b32 m0, s37
	ds_read_b128 v[204:207], v151 offset:54272
	global_load_lds_dwordx4 v128, s[100:101]
	s_mov_b32 m0, s38
	ds_read_b128 v[200:203], v151 offset:53248
	global_load_lds_dwordx4 v132, s[100:101]
	s_waitcnt vmcnt(8)
	s_waitcnt lgkmcnt(0)
	s_barrier
	s_waitcnt lgkmcnt(0)
	v_mfma_f32_16x16x32_bf16 v[60:63], v[152:155], v[184:187], v[60:63]
	v_mfma_f32_16x16x32_bf16 v[56:59], v[160:163], v[184:187], v[56:59]
	v_mfma_f32_16x16x32_bf16 v[52:55], v[152:155], v[192:195], v[52:55]
	v_mfma_f32_16x16x32_bf16 v[44:47], v[160:163], v[192:195], v[44:47]
	v_mfma_f32_16x16x32_bf16 v[36:39], v[152:155], v[200:203], v[36:39]
	v_mfma_f32_16x16x32_bf16 v[28:31], v[160:163], v[200:203], v[28:31]
	v_mfma_f32_16x16x32_bf16 v[20:23], v[152:155], v[208:211], v[20:23]
	v_mfma_f32_16x16x32_bf16 v[12:15], v[160:163], v[208:211], v[12:15]
	v_mfma_f32_16x16x32_bf16 v[60:63], v[156:159], v[188:191], v[60:63]
	v_mfma_f32_16x16x32_bf16 v[56:59], v[164:167], v[188:191], v[56:59]
	v_mfma_f32_16x16x32_bf16 v[52:55], v[156:159], v[196:199], v[52:55]
	v_mfma_f32_16x16x32_bf16 v[44:47], v[164:167], v[196:199], v[44:47]
	v_mfma_f32_16x16x32_bf16 v[36:39], v[156:159], v[204:207], v[36:39]
	v_mfma_f32_16x16x32_bf16 v[28:31], v[164:167], v[204:207], v[28:31]
	v_mfma_f32_16x16x32_bf16 v[20:23], v[156:159], v[212:215], v[20:23]
	v_mfma_f32_16x16x32_bf16 v[12:15], v[164:167], v[212:215], v[12:15]
	v_mfma_f32_16x16x32_bf16 v[48:51], v[168:171], v[184:187], v[48:51]
	v_mfma_f32_16x16x32_bf16 v[40:43], v[176:179], v[184:187], v[40:43]
	v_mfma_f32_16x16x32_bf16 v[32:35], v[168:171], v[192:195], v[32:35]
	v_mfma_f32_16x16x32_bf16 v[24:27], v[176:179], v[192:195], v[24:27]
	v_mfma_f32_16x16x32_bf16 v[16:19], v[168:171], v[200:203], v[16:19]
	v_mfma_f32_16x16x32_bf16 v[8:11], v[176:179], v[200:203], v[8:11]
	v_mfma_f32_16x16x32_bf16 v[4:7], v[168:171], v[208:211], v[4:7]
	v_mfma_f32_16x16x32_bf16 v[0:3], v[176:179], v[208:211], v[0:3]
	v_mfma_f32_16x16x32_bf16 v[48:51], v[172:175], v[188:191], v[48:51]
	v_mfma_f32_16x16x32_bf16 v[40:43], v[180:183], v[188:191], v[40:43]
	v_mfma_f32_16x16x32_bf16 v[32:35], v[172:175], v[196:199], v[32:35]
	v_mfma_f32_16x16x32_bf16 v[24:27], v[180:183], v[196:199], v[24:27]
	v_mfma_f32_16x16x32_bf16 v[16:19], v[172:175], v[204:207], v[16:19]
	v_mfma_f32_16x16x32_bf16 v[8:11], v[180:183], v[204:207], v[8:11]
	v_mfma_f32_16x16x32_bf16 v[4:7], v[172:175], v[212:215], v[4:7]
	v_mfma_f32_16x16x32_bf16 v[0:3], v[180:183], v[212:215], v[0:3]
	s_barrier
	s_add_i32 s58, s58, 2
	s_add_u32 s22, s22, 0x100
	s_addc_u32 s23, s23, 0
	s_add_u32 s56, s56, 0x100
	s_addc_u32 s57, s57, 0
	s_cmp_gt_u32 s58, 29
	s_cbranch_scc0 .LBB0_163
	s_and_b64 vcc, exec, s[10:11]
	s_cbranch_vccz .LBB0_166
	s_barrier

.LBB0_188:
	ds_read_b128 v[154:157], v149
	ds_read_b128 v[158:161], v149 offset:1024
	ds_read_b128 v[162:165], v149 offset:2048
	ds_read_b128 v[166:169], v149 offset:3072
	ds_read_b128 v[170:173], v150
	ds_read_b128 v[174:177], v150 offset:1024
	ds_read_b128 v[178:181], v150 offset:2048
	ds_read_b128 v[182:185], v150 offset:3072
	s_add_u32 s34, s30, 0xfff00080
	s_addc_u32 s35, s31, -1
	s_cmp_eq_u32 s79, 60
	s_cselect_b32 s37, s23, s35
	s_cselect_b32 s36, s73, s34
	s_cselect_b32 s35, s21, s78
	s_cselect_b32 s34, s74, s75
	s_add_u32 s98, s34, s10
	s_addc_u32 s99, s35, s11
	s_add_u32 s100, s36, s10
	s_addc_u32 s101, s37, s11
	s_add_i32 m0, s49, 0xc000
	ds_read_b128 v[186:189], v151
	ds_read_b128 v[190:193], v151 offset:1024
	ds_read_b128 v[194:197], v151 offset:2048
	ds_read_b128 v[198:201], v151 offset:3072
	ds_read_b128 v[202:205], v151 offset:4096
	ds_read_b128 v[206:209], v151 offset:5120
	ds_read_b128 v[210:213], v151 offset:6144
	global_load_lds_dwordx4 v136, s[30:31]
	s_add_i32 m0, s49, 0xe000
	ds_read_b128 v[214:217], v151 offset:7168
	global_load_lds_dwordx4 v138, s[30:31]
	s_waitcnt vmcnt(8)
	s_waitcnt lgkmcnt(0)
	s_barrier
	s_waitcnt lgkmcnt(0)
	v_mfma_f32_16x16x32_bf16 v[124:127], v[154:157], v[186:189], v[124:127]
	v_mfma_f32_16x16x32_bf16 v[120:123], v[162:165], v[186:189], v[120:123]
	v_mfma_f32_16x16x32_bf16 v[116:119], v[154:157], v[194:197], v[116:119]
	v_mfma_f32_16x16x32_bf16 v[112:115], v[162:165], v[194:197], v[112:115]
	v_mfma_f32_16x16x32_bf16 v[104:107], v[154:157], v[202:205], v[104:107]
	v_mfma_f32_16x16x32_bf16 v[96:99], v[162:165], v[202:205], v[96:99]
	v_mfma_f32_16x16x32_bf16 v[76:79], v[154:157], v[210:213], v[76:79]
	v_mfma_f32_16x16x32_bf16 v[72:75], v[162:165], v[210:213], v[72:75]
	v_mfma_f32_16x16x32_bf16 v[124:127], v[158:161], v[190:193], v[124:127]
	v_mfma_f32_16x16x32_bf16 v[120:123], v[166:169], v[190:193], v[120:123]
	v_mfma_f32_16x16x32_bf16 v[116:119], v[158:161], v[198:201], v[116:119]
	v_mfma_f32_16x16x32_bf16 v[112:115], v[166:169], v[198:201], v[112:115]
	v_mfma_f32_16x16x32_bf16 v[104:107], v[158:161], v[206:209], v[104:107]
	v_mfma_f32_16x16x32_bf16 v[96:99], v[166:169], v[206:209], v[96:99]
	v_mfma_f32_16x16x32_bf16 v[76:79], v[158:161], v[214:217], v[76:79]
	v_mfma_f32_16x16x32_bf16 v[72:75], v[166:169], v[214:217], v[72:75]
	v_mfma_f32_16x16x32_bf16 v[108:111], v[170:173], v[186:189], v[108:111]
	v_mfma_f32_16x16x32_bf16 v[100:103], v[178:181], v[186:189], v[100:103]
	v_mfma_f32_16x16x32_bf16 v[92:95], v[170:173], v[194:197], v[92:95]
	v_mfma_f32_16x16x32_bf16 v[88:91], v[178:181], v[194:197], v[88:91]
	v_mfma_f32_16x16x32_bf16 v[84:87], v[170:173], v[202:205], v[84:87]
	v_mfma_f32_16x16x32_bf16 v[80:83], v[178:181], v[202:205], v[80:83]
	v_mfma_f32_16x16x32_bf16 v[68:71], v[170:173], v[210:213], v[68:71]
	v_mfma_f32_16x16x32_bf16 v[64:67], v[178:181], v[210:213], v[64:67]
	v_mfma_f32_16x16x32_bf16 v[108:111], v[174:177], v[190:193], v[108:111]
	v_mfma_f32_16x16x32_bf16 v[100:103], v[182:185], v[190:193], v[100:103]
	v_mfma_f32_16x16x32_bf16 v[92:95], v[174:177], v[198:201], v[92:95]
	v_mfma_f32_16x16x32_bf16 v[88:91], v[182:185], v[198:201], v[88:91]
	v_mfma_f32_16x16x32_bf16 v[84:87], v[174:177], v[206:209], v[84:87]
	v_mfma_f32_16x16x32_bf16 v[80:83], v[182:185], v[206:209], v[80:83]
	v_mfma_f32_16x16x32_bf16 v[68:71], v[174:177], v[214:217], v[68:71]
	v_mfma_f32_16x16x32_bf16 v[64:67], v[182:185], v[214:217], v[64:67]
	s_barrier
	s_add_i32 s80, s63, s38
	s_mov_b32 m0, s80
	ds_read_b128 v[186:189], v151 offset:16384
	ds_read_b128 v[190:193], v151 offset:17408
	ds_read_b128 v[194:197], v151 offset:18432
	ds_read_b128 v[198:201], v151 offset:19456
	global_load_lds_dwordx4 v130, s[34:35]
	s_add_i32 m0, s80, 0x2000
	s_add_u32 s80, s34, 0x100000
	s_addc_u32 s81, s35, 0
	s_add_i32 s82, s68, s38
	global_load_lds_dwordx4 v134, s[34:35]
	s_mov_b32 m0, s82
	ds_read_b128 v[214:217], v151 offset:23552
	global_load_lds_dwordx4 v130, s[80:81]
	s_add_i32 m0, s82, 0x2000
	ds_read_b128 v[210:213], v151 offset:22528
	global_load_lds_dwordx4 v134, s[80:81]
	s_mov_b32 m0, s49
	ds_read_b128 v[206:209], v151 offset:21504
	global_load_lds_dwordx4 v128, s[36:37]
	s_mov_b32 m0, s54
	ds_read_b128 v[202:205], v151 offset:20480
	global_load_lds_dwordx4 v132, s[36:37]
	s_waitcnt vmcnt(8)
	s_waitcnt lgkmcnt(0)
	s_barrier
	s_waitcnt lgkmcnt(0)
	v_mfma_f32_16x16x32_bf16 v[60:63], v[154:157], v[186:189], v[60:63]
	v_mfma_f32_16x16x32_bf16 v[56:59], v[162:165], v[186:189], v[56:59]
	v_mfma_f32_16x16x32_bf16 v[44:47], v[154:157], v[194:197], v[44:47]
	v_mfma_f32_16x16x32_bf16 v[40:43], v[162:165], v[194:197], v[40:43]
	v_mfma_f32_16x16x32_bf16 v[28:31], v[154:157], v[202:205], v[28:31]
	v_mfma_f32_16x16x32_bf16 v[24:27], v[162:165], v[202:205], v[24:27]
	v_mfma_f32_16x16x32_bf16 v[12:15], v[154:157], v[210:213], v[12:15]
	v_mfma_f32_16x16x32_bf16 v[8:11], v[162:165], v[210:213], v[8:11]
	v_mfma_f32_16x16x32_bf16 v[60:63], v[158:161], v[190:193], v[60:63]
	v_mfma_f32_16x16x32_bf16 v[56:59], v[166:169], v[190:193], v[56:59]
	v_mfma_f32_16x16x32_bf16 v[44:47], v[158:161], v[198:201], v[44:47]
	v_mfma_f32_16x16x32_bf16 v[40:43], v[166:169], v[198:201], v[40:43]
	v_mfma_f32_16x16x32_bf16 v[28:31], v[158:161], v[206:209], v[28:31]
	v_mfma_f32_16x16x32_bf16 v[24:27], v[166:169], v[206:209], v[24:27]
	v_mfma_f32_16x16x32_bf16 v[12:15], v[158:161], v[214:217], v[12:15]
	v_mfma_f32_16x16x32_bf16 v[8:11], v[166:169], v[214:217], v[8:11]
	v_mfma_f32_16x16x32_bf16 v[52:55], v[170:173], v[186:189], v[52:55]
	v_mfma_f32_16x16x32_bf16 v[48:51], v[178:181], v[186:189], v[48:51]
	v_mfma_f32_16x16x32_bf16 v[36:39], v[170:173], v[194:197], v[36:39]
	v_mfma_f32_16x16x32_bf16 v[32:35], v[178:181], v[194:197], v[32:35]
	v_mfma_f32_16x16x32_bf16 v[20:23], v[170:173], v[202:205], v[20:23]
	v_mfma_f32_16x16x32_bf16 v[16:19], v[178:181], v[202:205], v[16:19]
	v_mfma_f32_16x16x32_bf16 v[4:7], v[170:173], v[210:213], v[4:7]
	v_mfma_f32_16x16x32_bf16 v[0:3], v[178:181], v[210:213], v[0:3]
	v_mfma_f32_16x16x32_bf16 v[52:55], v[174:177], v[190:193], v[52:55]
	v_mfma_f32_16x16x32_bf16 v[48:51], v[182:185], v[190:193], v[48:51]
	v_mfma_f32_16x16x32_bf16 v[36:39], v[174:177], v[198:201], v[36:39]
	v_mfma_f32_16x16x32_bf16 v[32:35], v[182:185], v[198:201], v[32:35]
	v_mfma_f32_16x16x32_bf16 v[20:23], v[174:177], v[206:209], v[20:23]
	v_mfma_f32_16x16x32_bf16 v[16:19], v[182:185], v[206:209], v[16:19]
	v_mfma_f32_16x16x32_bf16 v[4:7], v[174:177], v[214:217], v[4:7]
	v_mfma_f32_16x16x32_bf16 v[0:3], v[182:185], v[214:217], v[0:3]
	s_barrier
	s_add_i32 s80, 0, 0x18000
	s_add_i32 s81, 0, 0x1c000
	v_add_u32_e32 v166, s80, v147
	v_add_u32_e32 v182, s81, v147
	ds_read_b128 v[154:157], v166
	ds_read_b128 v[158:161], v166 offset:1024
	ds_read_b128 v[162:165], v166 offset:2048
	ds_read_b128 v[166:169], v166 offset:3072
	ds_read_b128 v[170:173], v182
	ds_read_b128 v[174:177], v182 offset:1024
	ds_read_b128 v[178:181], v182 offset:2048
	ds_read_b128 v[182:185], v182 offset:3072
	s_add_u32 s36, s36, 0x100000
	s_addc_u32 s37, s37, 0
	s_mov_b32 m0, s55
	ds_read_b128 v[186:189], v151 offset:32768
	ds_read_b128 v[190:193], v151 offset:33792
	ds_read_b128 v[194:197], v151 offset:34816
	ds_read_b128 v[198:201], v151 offset:35840
	ds_read_b128 v[202:205], v151 offset:36864
	ds_read_b128 v[206:209], v151 offset:37888
	ds_read_b128 v[210:213], v151 offset:38912
	global_load_lds_dwordx4 v128, s[36:37]
	s_mov_b32 m0, s56
	ds_read_b128 v[214:217], v151 offset:39936
	global_load_lds_dwordx4 v132, s[36:37]
	s_waitcnt vmcnt(8)
	s_waitcnt lgkmcnt(0)
	s_barrier
	s_waitcnt lgkmcnt(0)
	v_mfma_f32_16x16x32_bf16 v[124:127], v[154:157], v[186:189], v[124:127]
	v_mfma_f32_16x16x32_bf16 v[120:123], v[162:165], v[186:189], v[120:123]
	v_mfma_f32_16x16x32_bf16 v[116:119], v[154:157], v[194:197], v[116:119]
	v_mfma_f32_16x16x32_bf16 v[112:115], v[162:165], v[194:197], v[112:115]
	v_mfma_f32_16x16x32_bf16 v[104:107], v[154:157], v[202:205], v[104:107]
	v_mfma_f32_16x16x32_bf16 v[96:99], v[162:165], v[202:205], v[96:99]
	v_mfma_f32_16x16x32_bf16 v[76:79], v[154:157], v[210:213], v[76:79]
	v_mfma_f32_16x16x32_bf16 v[72:75], v[162:165], v[210:213], v[72:75]
	v_mfma_f32_16x16x32_bf16 v[124:127], v[158:161], v[190:193], v[124:127]
	v_mfma_f32_16x16x32_bf16 v[120:123], v[166:169], v[190:193], v[120:123]
	v_mfma_f32_16x16x32_bf16 v[116:119], v[158:161], v[198:201], v[116:119]
	v_mfma_f32_16x16x32_bf16 v[112:115], v[166:169], v[198:201], v[112:115]
	v_mfma_f32_16x16x32_bf16 v[104:107], v[158:161], v[206:209], v[104:107]
	v_mfma_f32_16x16x32_bf16 v[96:99], v[166:169], v[206:209], v[96:99]
	v_mfma_f32_16x16x32_bf16 v[76:79], v[158:161], v[214:217], v[76:79]
	v_mfma_f32_16x16x32_bf16 v[72:75], v[166:169], v[214:217], v[72:75]
	v_mfma_f32_16x16x32_bf16 v[108:111], v[170:173], v[186:189], v[108:111]
	v_mfma_f32_16x16x32_bf16 v[100:103], v[178:181], v[186:189], v[100:103]
	v_mfma_f32_16x16x32_bf16 v[92:95], v[170:173], v[194:197], v[92:95]
	v_mfma_f32_16x16x32_bf16 v[88:91], v[178:181], v[194:197], v[88:91]
	v_mfma_f32_16x16x32_bf16 v[84:87], v[170:173], v[202:205], v[84:87]
	v_mfma_f32_16x16x32_bf16 v[80:83], v[178:181], v[202:205], v[80:83]
	v_mfma_f32_16x16x32_bf16 v[68:71], v[170:173], v[210:213], v[68:71]
	v_mfma_f32_16x16x32_bf16 v[64:67], v[178:181], v[210:213], v[64:67]
	v_mfma_f32_16x16x32_bf16 v[108:111], v[174:177], v[190:193], v[108:111]
	v_mfma_f32_16x16x32_bf16 v[100:103], v[182:185], v[190:193], v[100:103]
	v_mfma_f32_16x16x32_bf16 v[92:95], v[174:177], v[198:201], v[92:95]
	v_mfma_f32_16x16x32_bf16 v[88:91], v[182:185], v[198:201], v[88:91]
	v_mfma_f32_16x16x32_bf16 v[84:87], v[174:177], v[206:209], v[84:87]
	v_mfma_f32_16x16x32_bf16 v[80:83], v[182:185], v[206:209], v[80:83]
	v_mfma_f32_16x16x32_bf16 v[68:71], v[174:177], v[214:217], v[68:71]
	v_mfma_f32_16x16x32_bf16 v[64:67], v[182:185], v[214:217], v[64:67]
	s_barrier
	s_add_i32 s36, s80, s38
	s_mov_b32 m0, s36
	ds_read_b128 v[186:189], v151 offset:49152
	ds_read_b128 v[190:193], v151 offset:50176
	ds_read_b128 v[194:197], v151 offset:51200
	ds_read_b128 v[198:201], v151 offset:52224
	global_load_lds_dwordx4 v130, s[98:99]
	s_add_i32 m0, s36, 0x2000
	s_add_u32 s34, s34, 0x100080
	s_addc_u32 s35, s35, 0
	s_add_i32 s36, s81, s38
	global_load_lds_dwordx4 v134, s[98:99]
	s_mov_b32 m0, s36
	ds_read_b128 v[214:217], v151 offset:56320
	global_load_lds_dwordx4 v130, s[34:35]
	s_add_i32 m0, s36, 0x2000
	ds_read_b128 v[210:213], v151 offset:55296
	global_load_lds_dwordx4 v134, s[34:35]
	s_mov_b32 m0, s58
	ds_read_b128 v[206:209], v151 offset:54272
	global_load_lds_dwordx4 v128, s[100:101]
	s_mov_b32 m0, s59
	ds_read_b128 v[202:205], v151 offset:53248
	global_load_lds_dwordx4 v132, s[100:101]
	s_waitcnt vmcnt(8)
	s_waitcnt lgkmcnt(0)
	s_barrier
	s_waitcnt lgkmcnt(0)
	v_mfma_f32_16x16x32_bf16 v[60:63], v[154:157], v[186:189], v[60:63]
	v_mfma_f32_16x16x32_bf16 v[56:59], v[162:165], v[186:189], v[56:59]
	v_mfma_f32_16x16x32_bf16 v[44:47], v[154:157], v[194:197], v[44:47]
	v_mfma_f32_16x16x32_bf16 v[40:43], v[162:165], v[194:197], v[40:43]
	v_mfma_f32_16x16x32_bf16 v[28:31], v[154:157], v[202:205], v[28:31]
	v_mfma_f32_16x16x32_bf16 v[24:27], v[162:165], v[202:205], v[24:27]
	v_mfma_f32_16x16x32_bf16 v[12:15], v[154:157], v[210:213], v[12:15]
	v_mfma_f32_16x16x32_bf16 v[8:11], v[162:165], v[210:213], v[8:11]
	v_mfma_f32_16x16x32_bf16 v[60:63], v[158:161], v[190:193], v[60:63]
	v_mfma_f32_16x16x32_bf16 v[56:59], v[166:169], v[190:193], v[56:59]
	v_mfma_f32_16x16x32_bf16 v[44:47], v[158:161], v[198:201], v[44:47]
	v_mfma_f32_16x16x32_bf16 v[40:43], v[166:169], v[198:201], v[40:43]
	v_mfma_f32_16x16x32_bf16 v[28:31], v[158:161], v[206:209], v[28:31]
	v_mfma_f32_16x16x32_bf16 v[24:27], v[166:169], v[206:209], v[24:27]
	v_mfma_f32_16x16x32_bf16 v[12:15], v[158:161], v[214:217], v[12:15]
	v_mfma_f32_16x16x32_bf16 v[8:11], v[166:169], v[214:217], v[8:11]
	v_mfma_f32_16x16x32_bf16 v[52:55], v[170:173], v[186:189], v[52:55]
	v_mfma_f32_16x16x32_bf16 v[48:51], v[178:181], v[186:189], v[48:51]
	v_mfma_f32_16x16x32_bf16 v[36:39], v[170:173], v[194:197], v[36:39]
	v_mfma_f32_16x16x32_bf16 v[32:35], v[178:181], v[194:197], v[32:35]
	v_mfma_f32_16x16x32_bf16 v[20:23], v[170:173], v[202:205], v[20:23]
	v_mfma_f32_16x16x32_bf16 v[16:19], v[178:181], v[202:205], v[16:19]
	v_mfma_f32_16x16x32_bf16 v[4:7], v[170:173], v[210:213], v[4:7]
	v_mfma_f32_16x16x32_bf16 v[0:3], v[178:181], v[210:213], v[0:3]
	v_mfma_f32_16x16x32_bf16 v[52:55], v[174:177], v[190:193], v[52:55]
	v_mfma_f32_16x16x32_bf16 v[48:51], v[182:185], v[190:193], v[48:51]
	v_mfma_f32_16x16x32_bf16 v[36:39], v[174:177], v[198:201], v[36:39]
	v_mfma_f32_16x16x32_bf16 v[32:35], v[182:185], v[198:201], v[32:35]
	v_mfma_f32_16x16x32_bf16 v[20:23], v[174:177], v[206:209], v[20:23]
	v_mfma_f32_16x16x32_bf16 v[16:19], v[182:185], v[206:209], v[16:19]
	v_mfma_f32_16x16x32_bf16 v[4:7], v[174:177], v[214:217], v[4:7]
	v_mfma_f32_16x16x32_bf16 v[0:3], v[182:185], v[214:217], v[0:3]
	s_barrier
	s_add_i32 s79, s79, 2
	s_add_u32 s30, s30, 0x100
	s_addc_u32 s31, s31, 0
	s_add_u32 s75, s75, 0x100
	s_addc_u32 s78, s78, 0
	s_cmp_gt_u32 s79, 61
	s_cbranch_scc0 .LBB0_188
	s_and_b64 vcc, exec, s[12:13]
	s_cbranch_vccz .LBB0_191
	s_barrier

.LBB0_431:
	ds_read_b128 v[128:131], v207
	ds_read_b128 v[132:135], v207 offset:1024
	ds_read_b128 v[136:139], v207 offset:2048
	ds_read_b128 v[140:143], v207 offset:3072
	ds_read_b128 v[144:147], v208
	ds_read_b128 v[148:151], v208 offset:1024
	ds_read_b128 v[152:155], v208 offset:2048
	ds_read_b128 v[156:159], v208 offset:3072
	s_add_u32 s28, s26, 0xfff00080
	s_addc_u32 s29, s27, -1
	s_cmp_eq_u32 s55, 60
	s_cselect_b32 s31, s15, s29
	s_cselect_b32 s30, s21, s28
	s_cselect_b32 s29, s13, s54
	s_cselect_b32 s28, s52, s53
	s_add_u32 s98, s28, s8
	s_addc_u32 s99, s29, s9
	s_add_u32 s100, s30, s8
	s_addc_u32 s101, s31, s9
	s_add_i32 m0, s23, 0xc000
	ds_read_b128 v[160:163], v209
	ds_read_b128 v[164:167], v209 offset:1024
	ds_read_b128 v[168:171], v209 offset:2048
	ds_read_b128 v[172:175], v209 offset:3072
	ds_read_b128 v[192:195], v209 offset:4096
	ds_read_b128 v[196:199], v209 offset:5120
	ds_read_b128 v[200:203], v209 offset:6144
	global_load_lds_dwordx4 v184, s[26:27]
	s_add_i32 m0, s23, 0xe000
	ds_read_b128 v[212:215], v209 offset:7168
	global_load_lds_dwordx4 v186, s[26:27]
	s_waitcnt vmcnt(8)
	s_waitcnt lgkmcnt(0)
	s_barrier
	s_waitcnt lgkmcnt(0)
	v_mfma_f32_16x16x32_bf16 v[124:127], v[128:131], v[160:163], v[124:127]
	v_mfma_f32_16x16x32_bf16 v[120:123], v[136:139], v[160:163], v[120:123]
	v_mfma_f32_16x16x32_bf16 v[108:111], v[128:131], v[168:171], v[108:111]
	v_mfma_f32_16x16x32_bf16 v[104:107], v[136:139], v[168:171], v[104:107]
	v_mfma_f32_16x16x32_bf16 v[92:95], v[128:131], v[192:195], v[92:95]
	v_mfma_f32_16x16x32_bf16 v[88:91], v[136:139], v[192:195], v[88:91]
	v_mfma_f32_16x16x32_bf16 v[76:79], v[128:131], v[200:203], v[76:79]
	v_mfma_f32_16x16x32_bf16 v[72:75], v[136:139], v[200:203], v[72:75]
	v_mfma_f32_16x16x32_bf16 v[124:127], v[132:135], v[164:167], v[124:127]
	v_mfma_f32_16x16x32_bf16 v[120:123], v[140:143], v[164:167], v[120:123]
	v_mfma_f32_16x16x32_bf16 v[108:111], v[132:135], v[172:175], v[108:111]
	v_mfma_f32_16x16x32_bf16 v[104:107], v[140:143], v[172:175], v[104:107]
	v_mfma_f32_16x16x32_bf16 v[92:95], v[132:135], v[196:199], v[92:95]
	v_mfma_f32_16x16x32_bf16 v[88:91], v[140:143], v[196:199], v[88:91]
	v_mfma_f32_16x16x32_bf16 v[76:79], v[132:135], v[212:215], v[76:79]
	v_mfma_f32_16x16x32_bf16 v[72:75], v[140:143], v[212:215], v[72:75]
	v_mfma_f32_16x16x32_bf16 v[116:119], v[144:147], v[160:163], v[116:119]
	v_mfma_f32_16x16x32_bf16 v[112:115], v[152:155], v[160:163], v[112:115]
	v_mfma_f32_16x16x32_bf16 v[100:103], v[144:147], v[168:171], v[100:103]
	v_mfma_f32_16x16x32_bf16 v[96:99], v[152:155], v[168:171], v[96:99]
	v_mfma_f32_16x16x32_bf16 v[84:87], v[144:147], v[192:195], v[84:87]
	v_mfma_f32_16x16x32_bf16 v[80:83], v[152:155], v[192:195], v[80:83]
	v_mfma_f32_16x16x32_bf16 v[68:71], v[144:147], v[200:203], v[68:71]
	v_mfma_f32_16x16x32_bf16 v[64:67], v[152:155], v[200:203], v[64:67]
	v_mfma_f32_16x16x32_bf16 v[116:119], v[148:151], v[164:167], v[116:119]
	v_mfma_f32_16x16x32_bf16 v[112:115], v[156:159], v[164:167], v[112:115]
	v_mfma_f32_16x16x32_bf16 v[100:103], v[148:151], v[172:175], v[100:103]
	v_mfma_f32_16x16x32_bf16 v[96:99], v[156:159], v[172:175], v[96:99]
	v_mfma_f32_16x16x32_bf16 v[84:87], v[148:151], v[196:199], v[84:87]
	v_mfma_f32_16x16x32_bf16 v[80:83], v[156:159], v[196:199], v[80:83]
	v_mfma_f32_16x16x32_bf16 v[68:71], v[148:151], v[212:215], v[68:71]
	v_mfma_f32_16x16x32_bf16 v[64:67], v[156:159], v[212:215], v[64:67]
	s_barrier
	s_add_i32 s58, s50, s3
	s_mov_b32 m0, s58
	ds_read_b128 v[160:163], v209 offset:16384
	ds_read_b128 v[164:167], v209 offset:17408
	ds_read_b128 v[168:171], v209 offset:18432
	ds_read_b128 v[172:175], v209 offset:19456
	global_load_lds_dwordx4 v178, s[28:29]
	s_add_i32 m0, s58, 0x2000
	s_add_u32 s58, s28, 0x100000
	s_addc_u32 s59, s29, 0
	s_add_i32 s62, s51, s3
	global_load_lds_dwordx4 v182, s[28:29]
	s_mov_b32 m0, s62
	ds_read_b128 v[212:215], v209 offset:23552
	global_load_lds_dwordx4 v178, s[58:59]
	s_add_i32 m0, s62, 0x2000
	ds_read_b128 v[200:203], v209 offset:22528
	global_load_lds_dwordx4 v182, s[58:59]
	s_mov_b32 m0, s23
	ds_read_b128 v[196:199], v209 offset:21504
	global_load_lds_dwordx4 v176, s[30:31]
	s_mov_b32 m0, s34
	ds_read_b128 v[192:195], v209 offset:20480
	global_load_lds_dwordx4 v180, s[30:31]
	s_waitcnt vmcnt(8)
	s_waitcnt lgkmcnt(0)
	s_barrier
	s_waitcnt lgkmcnt(0)
	v_mfma_f32_16x16x32_bf16 v[60:63], v[128:131], v[160:163], v[60:63]
	v_mfma_f32_16x16x32_bf16 v[56:59], v[136:139], v[160:163], v[56:59]
	v_mfma_f32_16x16x32_bf16 v[44:47], v[128:131], v[168:171], v[44:47]
	v_mfma_f32_16x16x32_bf16 v[40:43], v[136:139], v[168:171], v[40:43]
	v_mfma_f32_16x16x32_bf16 v[28:31], v[128:131], v[192:195], v[28:31]
	v_mfma_f32_16x16x32_bf16 v[24:27], v[136:139], v[192:195], v[24:27]
	v_mfma_f32_16x16x32_bf16 v[12:15], v[128:131], v[200:203], v[12:15]
	v_mfma_f32_16x16x32_bf16 v[8:11], v[136:139], v[200:203], v[8:11]
	v_mfma_f32_16x16x32_bf16 v[60:63], v[132:135], v[164:167], v[60:63]
	v_mfma_f32_16x16x32_bf16 v[56:59], v[140:143], v[164:167], v[56:59]
	v_mfma_f32_16x16x32_bf16 v[44:47], v[132:135], v[172:175], v[44:47]
	v_mfma_f32_16x16x32_bf16 v[40:43], v[140:143], v[172:175], v[40:43]
	v_mfma_f32_16x16x32_bf16 v[28:31], v[132:135], v[196:199], v[28:31]
	v_mfma_f32_16x16x32_bf16 v[24:27], v[140:143], v[196:199], v[24:27]
	v_mfma_f32_16x16x32_bf16 v[12:15], v[132:135], v[212:215], v[12:15]
	v_mfma_f32_16x16x32_bf16 v[8:11], v[140:143], v[212:215], v[8:11]
	v_mfma_f32_16x16x32_bf16 v[52:55], v[144:147], v[160:163], v[52:55]
	v_mfma_f32_16x16x32_bf16 v[48:51], v[152:155], v[160:163], v[48:51]
	v_mfma_f32_16x16x32_bf16 v[36:39], v[144:147], v[168:171], v[36:39]
	v_mfma_f32_16x16x32_bf16 v[32:35], v[152:155], v[168:171], v[32:35]
	v_mfma_f32_16x16x32_bf16 v[20:23], v[144:147], v[192:195], v[20:23]
	v_mfma_f32_16x16x32_bf16 v[16:19], v[152:155], v[192:195], v[16:19]
	v_mfma_f32_16x16x32_bf16 v[4:7], v[144:147], v[200:203], v[4:7]
	v_mfma_f32_16x16x32_bf16 v[0:3], v[152:155], v[200:203], v[0:3]
	v_mfma_f32_16x16x32_bf16 v[52:55], v[148:151], v[164:167], v[52:55]
	v_mfma_f32_16x16x32_bf16 v[48:51], v[156:159], v[164:167], v[48:51]
	v_mfma_f32_16x16x32_bf16 v[36:39], v[148:151], v[172:175], v[36:39]
	v_mfma_f32_16x16x32_bf16 v[32:35], v[156:159], v[172:175], v[32:35]
	v_mfma_f32_16x16x32_bf16 v[20:23], v[148:151], v[196:199], v[20:23]
	v_mfma_f32_16x16x32_bf16 v[16:19], v[156:159], v[196:199], v[16:19]
	v_mfma_f32_16x16x32_bf16 v[4:7], v[148:151], v[212:215], v[4:7]
	v_mfma_f32_16x16x32_bf16 v[0:3], v[156:159], v[212:215], v[0:3]
	s_barrier
	s_add_i32 s58, 0, 0x18000
	s_add_i32 s59, 0, 0x1c000
	v_add_u32_e32 v140, s58, v205
	v_add_u32_e32 v156, s59, v205
	ds_read_b128 v[128:131], v140
	ds_read_b128 v[132:135], v140 offset:1024
	ds_read_b128 v[136:139], v140 offset:2048
	ds_read_b128 v[140:143], v140 offset:3072
	ds_read_b128 v[144:147], v156
	ds_read_b128 v[148:151], v156 offset:1024
	ds_read_b128 v[152:155], v156 offset:2048
	ds_read_b128 v[156:159], v156 offset:3072
	s_add_u32 s30, s30, 0x100000
	s_addc_u32 s31, s31, 0
	s_mov_b32 m0, s35
	ds_read_b128 v[160:163], v209 offset:32768
	ds_read_b128 v[164:167], v209 offset:33792
	ds_read_b128 v[168:171], v209 offset:34816
	ds_read_b128 v[172:175], v209 offset:35840
	ds_read_b128 v[192:195], v209 offset:36864
	ds_read_b128 v[196:199], v209 offset:37888
	ds_read_b128 v[200:203], v209 offset:38912
	global_load_lds_dwordx4 v176, s[30:31]
	s_mov_b32 m0, s36
	ds_read_b128 v[212:215], v209 offset:39936
	global_load_lds_dwordx4 v180, s[30:31]
	s_waitcnt vmcnt(8)
	s_waitcnt lgkmcnt(0)
	s_barrier
	s_waitcnt lgkmcnt(0)
	v_mfma_f32_16x16x32_bf16 v[124:127], v[128:131], v[160:163], v[124:127]
	v_mfma_f32_16x16x32_bf16 v[120:123], v[136:139], v[160:163], v[120:123]
	v_mfma_f32_16x16x32_bf16 v[108:111], v[128:131], v[168:171], v[108:111]
	v_mfma_f32_16x16x32_bf16 v[104:107], v[136:139], v[168:171], v[104:107]
	v_mfma_f32_16x16x32_bf16 v[92:95], v[128:131], v[192:195], v[92:95]
	v_mfma_f32_16x16x32_bf16 v[88:91], v[136:139], v[192:195], v[88:91]
	v_mfma_f32_16x16x32_bf16 v[76:79], v[128:131], v[200:203], v[76:79]
	v_mfma_f32_16x16x32_bf16 v[72:75], v[136:139], v[200:203], v[72:75]
	v_mfma_f32_16x16x32_bf16 v[124:127], v[132:135], v[164:167], v[124:127]
	v_mfma_f32_16x16x32_bf16 v[120:123], v[140:143], v[164:167], v[120:123]
	v_mfma_f32_16x16x32_bf16 v[108:111], v[132:135], v[172:175], v[108:111]
	v_mfma_f32_16x16x32_bf16 v[104:107], v[140:143], v[172:175], v[104:107]
	v_mfma_f32_16x16x32_bf16 v[92:95], v[132:135], v[196:199], v[92:95]
	v_mfma_f32_16x16x32_bf16 v[88:91], v[140:143], v[196:199], v[88:91]
	v_mfma_f32_16x16x32_bf16 v[76:79], v[132:135], v[212:215], v[76:79]
	v_mfma_f32_16x16x32_bf16 v[72:75], v[140:143], v[212:215], v[72:75]
	v_mfma_f32_16x16x32_bf16 v[116:119], v[144:147], v[160:163], v[116:119]
	v_mfma_f32_16x16x32_bf16 v[112:115], v[152:155], v[160:163], v[112:115]
	v_mfma_f32_16x16x32_bf16 v[100:103], v[144:147], v[168:171], v[100:103]
	v_mfma_f32_16x16x32_bf16 v[96:99], v[152:155], v[168:171], v[96:99]
	v_mfma_f32_16x16x32_bf16 v[84:87], v[144:147], v[192:195], v[84:87]
	v_mfma_f32_16x16x32_bf16 v[80:83], v[152:155], v[192:195], v[80:83]
	v_mfma_f32_16x16x32_bf16 v[68:71], v[144:147], v[200:203], v[68:71]
	v_mfma_f32_16x16x32_bf16 v[64:67], v[152:155], v[200:203], v[64:67]
	v_mfma_f32_16x16x32_bf16 v[116:119], v[148:151], v[164:167], v[116:119]
	v_mfma_f32_16x16x32_bf16 v[112:115], v[156:159], v[164:167], v[112:115]
	v_mfma_f32_16x16x32_bf16 v[100:103], v[148:151], v[172:175], v[100:103]
	v_mfma_f32_16x16x32_bf16 v[96:99], v[156:159], v[172:175], v[96:99]
	v_mfma_f32_16x16x32_bf16 v[84:87], v[148:151], v[196:199], v[84:87]
	v_mfma_f32_16x16x32_bf16 v[80:83], v[156:159], v[196:199], v[80:83]
	v_mfma_f32_16x16x32_bf16 v[68:71], v[148:151], v[212:215], v[68:71]
	v_mfma_f32_16x16x32_bf16 v[64:67], v[156:159], v[212:215], v[64:67]
	s_barrier
	s_add_i32 s30, s58, s3
	s_mov_b32 m0, s30
	ds_read_b128 v[160:163], v209 offset:49152
	ds_read_b128 v[164:167], v209 offset:50176
	ds_read_b128 v[168:171], v209 offset:51200
	ds_read_b128 v[172:175], v209 offset:52224
	global_load_lds_dwordx4 v178, s[98:99]
	s_add_i32 m0, s30, 0x2000
	s_add_u32 s28, s28, 0x100080
	s_addc_u32 s29, s29, 0
	s_add_i32 s30, s59, s3
	global_load_lds_dwordx4 v182, s[98:99]
	s_mov_b32 m0, s30
	ds_read_b128 v[212:215], v209 offset:56320
	global_load_lds_dwordx4 v178, s[28:29]
	s_add_i32 m0, s30, 0x2000
	ds_read_b128 v[200:203], v209 offset:55296
	global_load_lds_dwordx4 v182, s[28:29]
	s_mov_b32 m0, s38
	ds_read_b128 v[196:199], v209 offset:54272
	global_load_lds_dwordx4 v176, s[100:101]
	s_mov_b32 m0, s39
	ds_read_b128 v[192:195], v209 offset:53248
	global_load_lds_dwordx4 v180, s[100:101]
	s_waitcnt vmcnt(8)
	s_waitcnt lgkmcnt(0)
	s_barrier
	s_waitcnt lgkmcnt(0)
	v_mfma_f32_16x16x32_bf16 v[60:63], v[128:131], v[160:163], v[60:63]
	v_mfma_f32_16x16x32_bf16 v[56:59], v[136:139], v[160:163], v[56:59]
	v_mfma_f32_16x16x32_bf16 v[44:47], v[128:131], v[168:171], v[44:47]
	v_mfma_f32_16x16x32_bf16 v[40:43], v[136:139], v[168:171], v[40:43]
	v_mfma_f32_16x16x32_bf16 v[28:31], v[128:131], v[192:195], v[28:31]
	v_mfma_f32_16x16x32_bf16 v[24:27], v[136:139], v[192:195], v[24:27]
	v_mfma_f32_16x16x32_bf16 v[12:15], v[128:131], v[200:203], v[12:15]
	v_mfma_f32_16x16x32_bf16 v[8:11], v[136:139], v[200:203], v[8:11]
	v_mfma_f32_16x16x32_bf16 v[60:63], v[132:135], v[164:167], v[60:63]
	v_mfma_f32_16x16x32_bf16 v[56:59], v[140:143], v[164:167], v[56:59]
	v_mfma_f32_16x16x32_bf16 v[44:47], v[132:135], v[172:175], v[44:47]
	v_mfma_f32_16x16x32_bf16 v[40:43], v[140:143], v[172:175], v[40:43]
	v_mfma_f32_16x16x32_bf16 v[28:31], v[132:135], v[196:199], v[28:31]
	v_mfma_f32_16x16x32_bf16 v[24:27], v[140:143], v[196:199], v[24:27]
	v_mfma_f32_16x16x32_bf16 v[12:15], v[132:135], v[212:215], v[12:15]
	v_mfma_f32_16x16x32_bf16 v[8:11], v[140:143], v[212:215], v[8:11]
	v_mfma_f32_16x16x32_bf16 v[52:55], v[144:147], v[160:163], v[52:55]
	v_mfma_f32_16x16x32_bf16 v[48:51], v[152:155], v[160:163], v[48:51]
	v_mfma_f32_16x16x32_bf16 v[36:39], v[144:147], v[168:171], v[36:39]
	v_mfma_f32_16x16x32_bf16 v[32:35], v[152:155], v[168:171], v[32:35]
	v_mfma_f32_16x16x32_bf16 v[20:23], v[144:147], v[192:195], v[20:23]
	v_mfma_f32_16x16x32_bf16 v[16:19], v[152:155], v[192:195], v[16:19]
	v_mfma_f32_16x16x32_bf16 v[4:7], v[144:147], v[200:203], v[4:7]
	v_mfma_f32_16x16x32_bf16 v[0:3], v[152:155], v[200:203], v[0:3]
	v_mfma_f32_16x16x32_bf16 v[52:55], v[148:151], v[164:167], v[52:55]
	v_mfma_f32_16x16x32_bf16 v[48:51], v[156:159], v[164:167], v[48:51]
	v_mfma_f32_16x16x32_bf16 v[36:39], v[148:151], v[172:175], v[36:39]
	v_mfma_f32_16x16x32_bf16 v[32:35], v[156:159], v[172:175], v[32:35]
	v_mfma_f32_16x16x32_bf16 v[20:23], v[148:151], v[196:199], v[20:23]
	v_mfma_f32_16x16x32_bf16 v[16:19], v[156:159], v[196:199], v[16:19]
	v_mfma_f32_16x16x32_bf16 v[4:7], v[148:151], v[212:215], v[4:7]
	v_mfma_f32_16x16x32_bf16 v[0:3], v[156:159], v[212:215], v[0:3]
	s_barrier
	s_add_i32 s55, s55, 2
	s_add_u32 s26, s26, 0x100
	s_addc_u32 s27, s27, 0
	s_add_u32 s53, s53, 0x100
	s_addc_u32 s54, s54, 0
	s_cmp_gt_u32 s55, 61
	s_cbranch_scc0 .LBB0_431
	s_and_b64 vcc, exec, s[10:11]
	s_cbranch_vccz .LBB0_434
	s_barrier

.LBB0_528:
	ds_read_b128 v[134:137], v200
	ds_read_b128 v[138:141], v200 offset:1024
	ds_read_b128 v[162:165], v200 offset:2048
	ds_read_b128 v[166:169], v200 offset:3072
	ds_read_b128 v[170:173], v201
	ds_read_b128 v[174:177], v201 offset:1024
	ds_read_b128 v[178:181], v201 offset:2048
	ds_read_b128 v[206:209], v201 offset:3072
	s_add_u32 s62, s20, 0xfff00080
	s_addc_u32 s63, s21, -1
	s_cmp_eq_u32 s83, 60
	s_cselect_b32 s79, s47, s63
	s_cselect_b32 s78, s57, s62
	s_cselect_b32 s63, s41, s82
	s_cselect_b32 s62, s59, s81
	s_add_u32 s98, s62, s30
	s_addc_u32 s99, s63, s31
	s_add_u32 s100, s78, s30
	s_addc_u32 s101, s79, s31
	s_add_i32 m0, s39, 0xc000
	ds_read_b128 v[210:213], v202
	ds_read_b128 v[214:217], v202 offset:1024
	ds_read_b128 v[218:221], v202 offset:2048
	ds_read_b128 v[222:225], v202 offset:3072
	ds_read_b128 v[226:229], v202 offset:4096
	ds_read_b128 v[230:233], v202 offset:5120
	ds_read_b128 v[234:237], v202 offset:6144
	global_load_lds_dwordx4 v154, s[20:21]
	s_add_i32 m0, s39, 0xe000
	ds_read_b128 v[238:241], v202 offset:7168
	global_load_lds_dwordx4 v156, s[20:21]
	s_waitcnt vmcnt(8)
	s_waitcnt lgkmcnt(0)
	s_barrier
	s_waitcnt lgkmcnt(0)
	v_mfma_f32_16x16x32_bf16 v[130:133], v[210:213], v[134:137], v[130:133]
	v_mfma_f32_16x16x32_bf16 v[126:129], v[210:213], v[162:165], v[126:129]
	v_mfma_f32_16x16x32_bf16 v[122:125], v[218:221], v[134:137], v[122:125]
	v_mfma_f32_16x16x32_bf16 v[118:121], v[218:221], v[162:165], v[118:121]
	v_mfma_f32_16x16x32_bf16 v[114:117], v[226:229], v[134:137], v[114:117]
	v_mfma_f32_16x16x32_bf16 v[110:113], v[226:229], v[162:165], v[110:113]
	v_mfma_f32_16x16x32_bf16 v[106:109], v[234:237], v[134:137], v[106:109]
	v_mfma_f32_16x16x32_bf16 v[102:105], v[234:237], v[162:165], v[102:105]
	v_mfma_f32_16x16x32_bf16 v[130:133], v[214:217], v[138:141], v[130:133]
	v_mfma_f32_16x16x32_bf16 v[126:129], v[214:217], v[166:169], v[126:129]
	v_mfma_f32_16x16x32_bf16 v[122:125], v[222:225], v[138:141], v[122:125]
	v_mfma_f32_16x16x32_bf16 v[118:121], v[222:225], v[166:169], v[118:121]
	v_mfma_f32_16x16x32_bf16 v[114:117], v[230:233], v[138:141], v[114:117]
	v_mfma_f32_16x16x32_bf16 v[110:113], v[230:233], v[166:169], v[110:113]
	v_mfma_f32_16x16x32_bf16 v[106:109], v[238:241], v[138:141], v[106:109]
	v_mfma_f32_16x16x32_bf16 v[102:105], v[238:241], v[166:169], v[102:105]
	v_mfma_f32_16x16x32_bf16 v[64:67], v[170:173], v[210:213], v[64:67]
	v_mfma_f32_16x16x32_bf16 v[60:63], v[178:181], v[210:213], v[60:63]
	v_mfma_f32_16x16x32_bf16 v[56:59], v[170:173], v[218:221], v[56:59]
	v_mfma_f32_16x16x32_bf16 v[52:55], v[178:181], v[218:221], v[52:55]
	v_mfma_f32_16x16x32_bf16 v[48:51], v[170:173], v[226:229], v[48:51]
	v_mfma_f32_16x16x32_bf16 v[44:47], v[178:181], v[226:229], v[44:47]
	v_mfma_f32_16x16x32_bf16 v[40:43], v[170:173], v[234:237], v[40:43]
	v_mfma_f32_16x16x32_bf16 v[36:39], v[178:181], v[234:237], v[36:39]
	v_mfma_f32_16x16x32_bf16 v[64:67], v[174:177], v[214:217], v[64:67]
	v_mfma_f32_16x16x32_bf16 v[60:63], v[206:209], v[214:217], v[60:63]
	v_mfma_f32_16x16x32_bf16 v[56:59], v[174:177], v[222:225], v[56:59]
	v_mfma_f32_16x16x32_bf16 v[52:55], v[206:209], v[222:225], v[52:55]
	v_mfma_f32_16x16x32_bf16 v[48:51], v[174:177], v[230:233], v[48:51]
	v_mfma_f32_16x16x32_bf16 v[44:47], v[206:209], v[230:233], v[44:47]
	v_mfma_f32_16x16x32_bf16 v[40:43], v[174:177], v[238:241], v[40:43]
	v_mfma_f32_16x16x32_bf16 v[36:39], v[206:209], v[238:241], v[36:39]
	s_barrier
	s_add_i32 s84, s75, s3
	s_mov_b32 m0, s84
	ds_read_b128 v[210:213], v202 offset:16384
	ds_read_b128 v[214:217], v202 offset:17408
	ds_read_b128 v[218:221], v202 offset:18432
	ds_read_b128 v[222:225], v202 offset:19456
	global_load_lds_dwordx4 v144, s[62:63]
	s_add_i32 m0, s84, 0x2000
	s_add_u32 s84, s62, 0x100000
	s_addc_u32 s85, s63, 0
	s_add_i32 s86, s80, s3
	global_load_lds_dwordx4 v148, s[62:63]
	s_mov_b32 m0, s86
	ds_read_b128 v[238:241], v202 offset:23552
	global_load_lds_dwordx4 v144, s[84:85]
	s_add_i32 m0, s86, 0x2000
	ds_read_b128 v[234:237], v202 offset:22528
	global_load_lds_dwordx4 v148, s[84:85]
	s_mov_b32 m0, s39
	ds_read_b128 v[230:233], v202 offset:21504
	global_load_lds_dwordx4 v142, s[78:79]
	s_mov_b32 m0, s54
	ds_read_b128 v[226:229], v202 offset:20480
	global_load_lds_dwordx4 v146, s[78:79]
	s_waitcnt vmcnt(8)
	s_waitcnt lgkmcnt(0)
	s_barrier
	s_waitcnt lgkmcnt(0)
	v_mfma_f32_16x16x32_bf16 v[98:101], v[210:213], v[134:137], v[98:101]
	v_mfma_f32_16x16x32_bf16 v[94:97], v[210:213], v[162:165], v[94:97]
	v_mfma_f32_16x16x32_bf16 v[90:93], v[218:221], v[134:137], v[90:93]
	v_mfma_f32_16x16x32_bf16 v[86:89], v[218:221], v[162:165], v[86:89]
	v_mfma_f32_16x16x32_bf16 v[82:85], v[226:229], v[134:137], v[82:85]
	v_mfma_f32_16x16x32_bf16 v[68:71], v[226:229], v[162:165], v[68:71]
	v_mfma_f32_16x16x32_bf16 v[72:75], v[234:237], v[134:137], v[74:77]
	v_mfma_f32_16x16x32_bf16 v[76:79], v[234:237], v[162:165], v[78:81]
	v_mfma_f32_16x16x32_bf16 v[98:101], v[214:217], v[138:141], v[98:101]
	v_mfma_f32_16x16x32_bf16 v[94:97], v[214:217], v[166:169], v[94:97]
	v_mfma_f32_16x16x32_bf16 v[90:93], v[222:225], v[138:141], v[90:93]
	v_mfma_f32_16x16x32_bf16 v[86:89], v[222:225], v[166:169], v[86:89]
	v_mfma_f32_16x16x32_bf16 v[82:85], v[230:233], v[138:141], v[82:85]
	v_mfma_f32_16x16x32_bf16 v[68:71], v[230:233], v[166:169], v[68:71]
	v_mfma_f32_16x16x32_bf16 v[72:75], v[238:241], v[138:141], v[72:75]
	v_mfma_f32_16x16x32_bf16 v[78:81], v[238:241], v[166:169], v[76:79]
	v_mfma_f32_16x16x32_bf16 v[32:35], v[170:173], v[210:213], v[32:35]
	v_mfma_f32_16x16x32_bf16 v[28:31], v[178:181], v[210:213], v[28:31]
	v_mfma_f32_16x16x32_bf16 v[24:27], v[170:173], v[218:221], v[24:27]
	v_mfma_f32_16x16x32_bf16 v[20:23], v[178:181], v[218:221], v[20:23]
	v_mfma_f32_16x16x32_bf16 v[16:19], v[170:173], v[226:229], v[16:19]
	v_mfma_f32_16x16x32_bf16 v[12:15], v[178:181], v[226:229], v[12:15]
	v_mfma_f32_16x16x32_bf16 v[2:5], v[170:173], v[234:237], v[4:7]
	v_mfma_f32_16x16x32_bf16 v[6:9], v[178:181], v[234:237], v[8:11]
	v_mfma_f32_16x16x32_bf16 v[32:35], v[174:177], v[214:217], v[32:35]
	v_mfma_f32_16x16x32_bf16 v[28:31], v[206:209], v[214:217], v[28:31]
	v_mfma_f32_16x16x32_bf16 v[24:27], v[174:177], v[222:225], v[24:27]
	v_mfma_f32_16x16x32_bf16 v[20:23], v[206:209], v[222:225], v[20:23]
	v_mfma_f32_16x16x32_bf16 v[16:19], v[174:177], v[230:233], v[16:19]
	v_mfma_f32_16x16x32_bf16 v[12:15], v[206:209], v[230:233], v[12:15]
	v_mfma_f32_16x16x32_bf16 v[2:5], v[174:177], v[238:241], v[2:5]
	v_mfma_f32_16x16x32_bf16 v[8:11], v[206:209], v[238:241], v[6:9]
	s_barrier
	s_add_i32 s84, 0, 0x18000
	v_add_u32_e32 v1, s84, v183
	s_add_i32 s85, 0, 0x1c000
	ds_read_b128 v[134:137], v1
	ds_read_b128 v[138:141], v1 offset:1024
	ds_read_b128 v[162:165], v1 offset:2048
	ds_read_b128 v[166:169], v1 offset:3072
	v_add_u32_e32 v1, s85, v183
	ds_read_b128 v[170:173], v1
	ds_read_b128 v[174:177], v1 offset:1024
	ds_read_b128 v[178:181], v1 offset:2048
	ds_read_b128 v[206:209], v1 offset:3072
	s_add_u32 s78, s78, 0x100000
	s_addc_u32 s79, s79, 0
	s_mov_b32 m0, s55
	ds_read_b128 v[210:213], v202 offset:32768
	ds_read_b128 v[214:217], v202 offset:33792
	ds_read_b128 v[218:221], v202 offset:34816
	ds_read_b128 v[222:225], v202 offset:35840
	ds_read_b128 v[226:229], v202 offset:36864
	ds_read_b128 v[230:233], v202 offset:37888
	ds_read_b128 v[234:237], v202 offset:38912
	global_load_lds_dwordx4 v142, s[78:79]
	s_mov_b32 m0, s68
	ds_read_b128 v[238:241], v202 offset:39936
	global_load_lds_dwordx4 v146, s[78:79]
	s_waitcnt vmcnt(8)
	s_waitcnt lgkmcnt(0)
	s_barrier
	s_waitcnt lgkmcnt(0)
	v_mfma_f32_16x16x32_bf16 v[130:133], v[210:213], v[134:137], v[130:133]
	v_mfma_f32_16x16x32_bf16 v[126:129], v[210:213], v[162:165], v[126:129]
	v_mfma_f32_16x16x32_bf16 v[122:125], v[218:221], v[134:137], v[122:125]
	v_mfma_f32_16x16x32_bf16 v[118:121], v[218:221], v[162:165], v[118:121]
	v_mfma_f32_16x16x32_bf16 v[114:117], v[226:229], v[134:137], v[114:117]
	v_mfma_f32_16x16x32_bf16 v[110:113], v[226:229], v[162:165], v[110:113]
	v_mfma_f32_16x16x32_bf16 v[106:109], v[234:237], v[134:137], v[106:109]
	v_mfma_f32_16x16x32_bf16 v[102:105], v[234:237], v[162:165], v[102:105]
	v_mfma_f32_16x16x32_bf16 v[130:133], v[214:217], v[138:141], v[130:133]
	v_mfma_f32_16x16x32_bf16 v[126:129], v[214:217], v[166:169], v[126:129]
	v_mfma_f32_16x16x32_bf16 v[122:125], v[222:225], v[138:141], v[122:125]
	v_mfma_f32_16x16x32_bf16 v[118:121], v[222:225], v[166:169], v[118:121]
	v_mfma_f32_16x16x32_bf16 v[114:117], v[230:233], v[138:141], v[114:117]
	v_mfma_f32_16x16x32_bf16 v[110:113], v[230:233], v[166:169], v[110:113]
	v_mfma_f32_16x16x32_bf16 v[106:109], v[238:241], v[138:141], v[106:109]
	v_mfma_f32_16x16x32_bf16 v[102:105], v[238:241], v[166:169], v[102:105]
	v_mfma_f32_16x16x32_bf16 v[64:67], v[170:173], v[210:213], v[64:67]
	v_mfma_f32_16x16x32_bf16 v[60:63], v[178:181], v[210:213], v[60:63]
	v_mfma_f32_16x16x32_bf16 v[56:59], v[170:173], v[218:221], v[56:59]
	v_mfma_f32_16x16x32_bf16 v[52:55], v[178:181], v[218:221], v[52:55]
	v_mfma_f32_16x16x32_bf16 v[48:51], v[170:173], v[226:229], v[48:51]
	v_mfma_f32_16x16x32_bf16 v[44:47], v[178:181], v[226:229], v[44:47]
	v_mfma_f32_16x16x32_bf16 v[40:43], v[170:173], v[234:237], v[40:43]
	v_mfma_f32_16x16x32_bf16 v[36:39], v[178:181], v[234:237], v[36:39]
	v_mfma_f32_16x16x32_bf16 v[64:67], v[174:177], v[214:217], v[64:67]
	v_mfma_f32_16x16x32_bf16 v[60:63], v[206:209], v[214:217], v[60:63]
	v_mfma_f32_16x16x32_bf16 v[56:59], v[174:177], v[222:225], v[56:59]
	v_mfma_f32_16x16x32_bf16 v[52:55], v[206:209], v[222:225], v[52:55]
	v_mfma_f32_16x16x32_bf16 v[48:51], v[174:177], v[230:233], v[48:51]
	v_mfma_f32_16x16x32_bf16 v[44:47], v[206:209], v[230:233], v[44:47]
	v_mfma_f32_16x16x32_bf16 v[40:43], v[174:177], v[238:241], v[40:43]
	v_mfma_f32_16x16x32_bf16 v[36:39], v[206:209], v[238:241], v[36:39]
	s_barrier
	s_add_i32 s78, s84, s3
	s_mov_b32 m0, s78
	ds_read_b128 v[210:213], v202 offset:49152
	ds_read_b128 v[214:217], v202 offset:50176
	ds_read_b128 v[218:221], v202 offset:51200
	ds_read_b128 v[222:225], v202 offset:52224
	global_load_lds_dwordx4 v144, s[98:99]
	s_add_i32 m0, s78, 0x2000
	s_add_u32 s62, s62, 0x100080
	s_addc_u32 s63, s63, 0
	s_add_i32 s78, s85, s3
	global_load_lds_dwordx4 v148, s[98:99]
	s_mov_b32 m0, s78
	ds_read_b128 v[238:241], v202 offset:56320
	global_load_lds_dwordx4 v144, s[62:63]
	s_add_i32 m0, s78, 0x2000
	ds_read_b128 v[234:237], v202 offset:55296
	global_load_lds_dwordx4 v148, s[62:63]
	s_mov_b32 m0, s71
	ds_read_b128 v[230:233], v202 offset:54272
	global_load_lds_dwordx4 v142, s[100:101]
	s_mov_b32 m0, s72
	ds_read_b128 v[226:229], v202 offset:53248
	global_load_lds_dwordx4 v146, s[100:101]
	s_waitcnt vmcnt(8)
	s_waitcnt lgkmcnt(0)
	s_barrier
	s_waitcnt lgkmcnt(0)
	v_mfma_f32_16x16x32_bf16 v[98:101], v[210:213], v[134:137], v[98:101]
	v_mfma_f32_16x16x32_bf16 v[94:97], v[210:213], v[162:165], v[94:97]
	v_mfma_f32_16x16x32_bf16 v[90:93], v[218:221], v[134:137], v[90:93]
	v_mfma_f32_16x16x32_bf16 v[86:89], v[218:221], v[162:165], v[86:89]
	v_mfma_f32_16x16x32_bf16 v[82:85], v[226:229], v[134:137], v[82:85]
	v_mfma_f32_16x16x32_bf16 v[68:71], v[226:229], v[162:165], v[68:71]
	v_mfma_f32_16x16x32_bf16 v[72:75], v[234:237], v[134:137], v[72:75]
	v_mfma_f32_16x16x32_bf16 v[78:81], v[234:237], v[162:165], v[78:81]
	v_mfma_f32_16x16x32_bf16 v[98:101], v[214:217], v[138:141], v[98:101]
	v_mfma_f32_16x16x32_bf16 v[94:97], v[214:217], v[166:169], v[94:97]
	v_mfma_f32_16x16x32_bf16 v[90:93], v[222:225], v[138:141], v[90:93]
	v_mfma_f32_16x16x32_bf16 v[86:89], v[222:225], v[166:169], v[86:89]
	v_mfma_f32_16x16x32_bf16 v[82:85], v[230:233], v[138:141], v[82:85]
	v_mfma_f32_16x16x32_bf16 v[68:71], v[230:233], v[166:169], v[68:71]
	v_mfma_f32_16x16x32_bf16 v[74:77], v[238:241], v[138:141], v[72:75]
	v_mfma_f32_16x16x32_bf16 v[78:81], v[238:241], v[166:169], v[78:81]
	v_mfma_f32_16x16x32_bf16 v[32:35], v[170:173], v[210:213], v[32:35]
	v_mfma_f32_16x16x32_bf16 v[28:31], v[178:181], v[210:213], v[28:31]
	v_mfma_f32_16x16x32_bf16 v[24:27], v[170:173], v[218:221], v[24:27]
	v_mfma_f32_16x16x32_bf16 v[20:23], v[178:181], v[218:221], v[20:23]
	v_mfma_f32_16x16x32_bf16 v[16:19], v[170:173], v[226:229], v[16:19]
	v_mfma_f32_16x16x32_bf16 v[12:15], v[178:181], v[226:229], v[12:15]
	v_mfma_f32_16x16x32_bf16 v[2:5], v[170:173], v[234:237], v[2:5]
	v_mfma_f32_16x16x32_bf16 v[8:11], v[178:181], v[234:237], v[8:11]
	v_mfma_f32_16x16x32_bf16 v[32:35], v[174:177], v[214:217], v[32:35]
	v_mfma_f32_16x16x32_bf16 v[28:31], v[206:209], v[214:217], v[28:31]
	v_mfma_f32_16x16x32_bf16 v[24:27], v[174:177], v[222:225], v[24:27]
	v_mfma_f32_16x16x32_bf16 v[20:23], v[206:209], v[222:225], v[20:23]
	v_mfma_f32_16x16x32_bf16 v[16:19], v[174:177], v[230:233], v[16:19]
	v_mfma_f32_16x16x32_bf16 v[12:15], v[206:209], v[230:233], v[12:15]
	v_mfma_f32_16x16x32_bf16 v[4:7], v[174:177], v[238:241], v[2:5]
	v_mfma_f32_16x16x32_bf16 v[8:11], v[206:209], v[238:241], v[8:11]
	s_barrier
	s_add_i32 s83, s83, 2
	s_add_u32 s20, s20, 0x100
	s_addc_u32 s21, s21, 0
	s_add_u32 s81, s81, 0x100
	s_addc_u32 s82, s82, 0
	s_cmp_gt_u32 s83, 61
	s_cbranch_scc0 .LBB0_528
	s_and_b64 vcc, exec, s[34:35]
	s_cbranch_vccz .LBB0_531
	s_barrier

.LBB0_815:
	ds_read_b128 v[56:59], v241
	ds_read_b128 v[60:63], v241 offset:1024
	ds_read_b128 v[64:67], v241 offset:2048
	ds_read_b128 v[68:71], v241 offset:3072
	ds_read_b128 v[144:147], v242
	ds_read_b128 v[148:151], v242 offset:1024
	ds_read_b128 v[152:155], v242 offset:2048
	ds_read_b128 v[156:159], v242 offset:3072
	s_add_u32 s50, s46, 0xffe00080
	s_addc_u32 s51, s47, -1
	s_cmpk_eq_i32 s77, 0x7c
	s_cselect_b32 s53, s29, s51
	s_cselect_b32 s52, s39, s50
	s_cselect_b32 s51, s31, s76
	s_cselect_b32 s50, s41, s75
	s_add_u32 s98, s50, s12
	s_addc_u32 s99, s51, s13
	s_add_u32 s100, s52, s12
	s_addc_u32 s101, s53, s13
	s_add_i32 m0, s55, 0xc000
	ds_read_b128 v[160:163], v243
	ds_read_b128 v[164:167], v243 offset:1024
	ds_read_b128 v[168:171], v243 offset:2048
	ds_read_b128 v[172:175], v243 offset:3072
	ds_read_b128 v[176:179], v243 offset:4096
	ds_read_b128 v[180:183], v243 offset:5120
	ds_read_b128 v[184:187], v243 offset:6144
	global_load_lds_dwordx4 v216, s[46:47]
	s_add_i32 m0, s55, 0xe000
	ds_read_b128 v[188:191], v243 offset:7168
	global_load_lds_dwordx4 v218, s[46:47]
	s_waitcnt vmcnt(8)
	s_waitcnt lgkmcnt(0)
	s_barrier
	s_waitcnt lgkmcnt(0)
	v_mfma_f32_16x16x32_bf16 v[140:143], v[56:59], v[160:163], v[140:143]
	v_mfma_f32_16x16x32_bf16 v[136:139], v[64:67], v[160:163], v[136:139]
	v_mfma_f32_16x16x32_bf16 v[124:127], v[56:59], v[168:171], v[124:127]
	v_mfma_f32_16x16x32_bf16 v[120:123], v[64:67], v[168:171], v[120:123]
	v_mfma_f32_16x16x32_bf16 v[108:111], v[56:59], v[176:179], v[108:111]
	v_mfma_f32_16x16x32_bf16 v[104:107], v[64:67], v[176:179], v[104:107]
	v_mfma_f32_16x16x32_bf16 v[92:95], v[56:59], v[184:187], v[92:95]
	v_mfma_f32_16x16x32_bf16 v[88:91], v[64:67], v[184:187], v[88:91]
	v_mfma_f32_16x16x32_bf16 v[140:143], v[60:63], v[164:167], v[140:143]
	v_mfma_f32_16x16x32_bf16 v[136:139], v[68:71], v[164:167], v[136:139]
	v_mfma_f32_16x16x32_bf16 v[124:127], v[60:63], v[172:175], v[124:127]
	v_mfma_f32_16x16x32_bf16 v[120:123], v[68:71], v[172:175], v[120:123]
	v_mfma_f32_16x16x32_bf16 v[108:111], v[60:63], v[180:183], v[108:111]
	v_mfma_f32_16x16x32_bf16 v[104:107], v[68:71], v[180:183], v[104:107]
	v_mfma_f32_16x16x32_bf16 v[92:95], v[60:63], v[188:191], v[92:95]
	v_mfma_f32_16x16x32_bf16 v[88:91], v[68:71], v[188:191], v[88:91]
	v_mfma_f32_16x16x32_bf16 v[132:135], v[144:147], v[160:163], v[132:135]
	v_mfma_f32_16x16x32_bf16 v[128:131], v[152:155], v[160:163], v[128:131]
	v_mfma_f32_16x16x32_bf16 v[116:119], v[144:147], v[168:171], v[116:119]
	v_mfma_f32_16x16x32_bf16 v[112:115], v[152:155], v[168:171], v[112:115]
	v_mfma_f32_16x16x32_bf16 v[100:103], v[144:147], v[176:179], v[100:103]
	v_mfma_f32_16x16x32_bf16 v[96:99], v[152:155], v[176:179], v[96:99]
	v_mfma_f32_16x16x32_bf16 v[84:87], v[144:147], v[184:187], v[84:87]
	v_mfma_f32_16x16x32_bf16 v[80:83], v[152:155], v[184:187], v[80:83]
	v_mfma_f32_16x16x32_bf16 v[132:135], v[148:151], v[164:167], v[132:135]
	v_mfma_f32_16x16x32_bf16 v[128:131], v[156:159], v[164:167], v[128:131]
	v_mfma_f32_16x16x32_bf16 v[116:119], v[148:151], v[172:175], v[116:119]
	v_mfma_f32_16x16x32_bf16 v[112:115], v[156:159], v[172:175], v[112:115]
	v_mfma_f32_16x16x32_bf16 v[100:103], v[148:151], v[180:183], v[100:103]
	v_mfma_f32_16x16x32_bf16 v[96:99], v[156:159], v[180:183], v[96:99]
	v_mfma_f32_16x16x32_bf16 v[84:87], v[148:151], v[188:191], v[84:87]
	v_mfma_f32_16x16x32_bf16 v[80:83], v[156:159], v[188:191], v[80:83]
	s_barrier
	s_add_i32 s78, s73, s54
	s_mov_b32 m0, s78
	ds_read_b128 v[160:163], v243 offset:16384
	ds_read_b128 v[164:167], v243 offset:17408
	ds_read_b128 v[168:171], v243 offset:18432
	ds_read_b128 v[172:175], v243 offset:19456
	global_load_lds_dwordx4 v210, s[50:51]
	s_add_i32 m0, s78, 0x2000
	s_add_u32 s78, s50, 0x200000
	s_addc_u32 s79, s51, 0
	s_add_i32 s80, s74, s54
	global_load_lds_dwordx4 v214, s[50:51]
	s_mov_b32 m0, s80
	ds_read_b128 v[188:191], v243 offset:23552
	global_load_lds_dwordx4 v210, s[78:79]
	s_add_i32 m0, s80, 0x2000
	ds_read_b128 v[184:187], v243 offset:22528
	global_load_lds_dwordx4 v214, s[78:79]
	s_mov_b32 m0, s55
	ds_read_b128 v[180:183], v243 offset:21504
	global_load_lds_dwordx4 v208, s[52:53]
	s_mov_b32 m0, s56
	ds_read_b128 v[176:179], v243 offset:20480
	global_load_lds_dwordx4 v212, s[52:53]
	s_waitcnt vmcnt(8)
	s_waitcnt lgkmcnt(0)
	s_barrier
	s_waitcnt lgkmcnt(0)
	v_mfma_f32_16x16x32_bf16 v[76:79], v[56:59], v[160:163], v[76:79]
	v_mfma_f32_16x16x32_bf16 v[72:75], v[64:67], v[160:163], v[72:75]
	v_mfma_f32_16x16x32_bf16 v[44:47], v[56:59], v[168:171], v[44:47]
	v_mfma_f32_16x16x32_bf16 v[40:43], v[64:67], v[168:171], v[40:43]
	v_mfma_f32_16x16x32_bf16 v[28:31], v[56:59], v[176:179], v[28:31]
	v_mfma_f32_16x16x32_bf16 v[24:27], v[64:67], v[176:179], v[24:27]
	v_mfma_f32_16x16x32_bf16 v[12:15], v[56:59], v[184:187], v[12:15]
	v_mfma_f32_16x16x32_bf16 v[8:11], v[64:67], v[184:187], v[8:11]
	v_mfma_f32_16x16x32_bf16 v[76:79], v[60:63], v[164:167], v[76:79]
	v_mfma_f32_16x16x32_bf16 v[72:75], v[68:71], v[164:167], v[72:75]
	v_mfma_f32_16x16x32_bf16 v[44:47], v[60:63], v[172:175], v[44:47]
	v_mfma_f32_16x16x32_bf16 v[40:43], v[68:71], v[172:175], v[40:43]
	v_mfma_f32_16x16x32_bf16 v[28:31], v[60:63], v[180:183], v[28:31]
	v_mfma_f32_16x16x32_bf16 v[24:27], v[68:71], v[180:183], v[24:27]
	v_mfma_f32_16x16x32_bf16 v[12:15], v[60:63], v[188:191], v[12:15]
	v_mfma_f32_16x16x32_bf16 v[8:11], v[68:71], v[188:191], v[8:11]
	v_mfma_f32_16x16x32_bf16 v[52:55], v[144:147], v[160:163], v[52:55]
	v_mfma_f32_16x16x32_bf16 v[48:51], v[152:155], v[160:163], v[48:51]
	v_mfma_f32_16x16x32_bf16 v[36:39], v[144:147], v[168:171], v[36:39]
	v_mfma_f32_16x16x32_bf16 v[32:35], v[152:155], v[168:171], v[32:35]
	v_mfma_f32_16x16x32_bf16 v[20:23], v[144:147], v[176:179], v[20:23]
	v_mfma_f32_16x16x32_bf16 v[16:19], v[152:155], v[176:179], v[16:19]
	v_mfma_f32_16x16x32_bf16 v[4:7], v[144:147], v[184:187], v[4:7]
	v_mfma_f32_16x16x32_bf16 v[0:3], v[152:155], v[184:187], v[0:3]
	v_mfma_f32_16x16x32_bf16 v[52:55], v[148:151], v[164:167], v[52:55]
	v_mfma_f32_16x16x32_bf16 v[48:51], v[156:159], v[164:167], v[48:51]
	v_mfma_f32_16x16x32_bf16 v[36:39], v[148:151], v[172:175], v[36:39]
	v_mfma_f32_16x16x32_bf16 v[32:35], v[156:159], v[172:175], v[32:35]
	v_mfma_f32_16x16x32_bf16 v[20:23], v[148:151], v[180:183], v[20:23]
	v_mfma_f32_16x16x32_bf16 v[16:19], v[156:159], v[180:183], v[16:19]
	v_mfma_f32_16x16x32_bf16 v[4:7], v[148:151], v[188:191], v[4:7]
	v_mfma_f32_16x16x32_bf16 v[0:3], v[156:159], v[188:191], v[0:3]
	s_barrier
	s_add_i32 s78, 0, 0x18000
	s_add_i32 s79, 0, 0x1c000
	v_add_u32_e32 v68, s78, v239
	v_add_u32_e32 v156, s79, v239
	ds_read_b128 v[56:59], v68
	ds_read_b128 v[60:63], v68 offset:1024
	ds_read_b128 v[64:67], v68 offset:2048
	ds_read_b128 v[68:71], v68 offset:3072
	ds_read_b128 v[144:147], v156
	ds_read_b128 v[148:151], v156 offset:1024
	ds_read_b128 v[152:155], v156 offset:2048
	ds_read_b128 v[156:159], v156 offset:3072
	s_add_u32 s52, s52, 0x200000
	s_addc_u32 s53, s53, 0
	s_mov_b32 m0, s57
	ds_read_b128 v[160:163], v243 offset:32768
	ds_read_b128 v[164:167], v243 offset:33792
	ds_read_b128 v[168:171], v243 offset:34816
	ds_read_b128 v[172:175], v243 offset:35840
	ds_read_b128 v[176:179], v243 offset:36864
	ds_read_b128 v[180:183], v243 offset:37888
	ds_read_b128 v[184:187], v243 offset:38912
	global_load_lds_dwordx4 v208, s[52:53]
	s_mov_b32 m0, s58
	ds_read_b128 v[188:191], v243 offset:39936
	global_load_lds_dwordx4 v212, s[52:53]
	s_waitcnt vmcnt(8)
	s_waitcnt lgkmcnt(0)
	s_barrier
	s_waitcnt lgkmcnt(0)
	v_mfma_f32_16x16x32_bf16 v[140:143], v[56:59], v[160:163], v[140:143]
	v_mfma_f32_16x16x32_bf16 v[136:139], v[64:67], v[160:163], v[136:139]
	v_mfma_f32_16x16x32_bf16 v[124:127], v[56:59], v[168:171], v[124:127]
	v_mfma_f32_16x16x32_bf16 v[120:123], v[64:67], v[168:171], v[120:123]
	v_mfma_f32_16x16x32_bf16 v[108:111], v[56:59], v[176:179], v[108:111]
	v_mfma_f32_16x16x32_bf16 v[104:107], v[64:67], v[176:179], v[104:107]
	v_mfma_f32_16x16x32_bf16 v[92:95], v[56:59], v[184:187], v[92:95]
	v_mfma_f32_16x16x32_bf16 v[88:91], v[64:67], v[184:187], v[88:91]
	v_mfma_f32_16x16x32_bf16 v[140:143], v[60:63], v[164:167], v[140:143]
	v_mfma_f32_16x16x32_bf16 v[136:139], v[68:71], v[164:167], v[136:139]
	v_mfma_f32_16x16x32_bf16 v[124:127], v[60:63], v[172:175], v[124:127]
	v_mfma_f32_16x16x32_bf16 v[120:123], v[68:71], v[172:175], v[120:123]
	v_mfma_f32_16x16x32_bf16 v[108:111], v[60:63], v[180:183], v[108:111]
	v_mfma_f32_16x16x32_bf16 v[104:107], v[68:71], v[180:183], v[104:107]
	v_mfma_f32_16x16x32_bf16 v[92:95], v[60:63], v[188:191], v[92:95]
	v_mfma_f32_16x16x32_bf16 v[88:91], v[68:71], v[188:191], v[88:91]
	v_mfma_f32_16x16x32_bf16 v[132:135], v[144:147], v[160:163], v[132:135]
	v_mfma_f32_16x16x32_bf16 v[128:131], v[152:155], v[160:163], v[128:131]
	v_mfma_f32_16x16x32_bf16 v[116:119], v[144:147], v[168:171], v[116:119]
	v_mfma_f32_16x16x32_bf16 v[112:115], v[152:155], v[168:171], v[112:115]
	v_mfma_f32_16x16x32_bf16 v[100:103], v[144:147], v[176:179], v[100:103]
	v_mfma_f32_16x16x32_bf16 v[96:99], v[152:155], v[176:179], v[96:99]
	v_mfma_f32_16x16x32_bf16 v[84:87], v[144:147], v[184:187], v[84:87]
	v_mfma_f32_16x16x32_bf16 v[80:83], v[152:155], v[184:187], v[80:83]
	v_mfma_f32_16x16x32_bf16 v[132:135], v[148:151], v[164:167], v[132:135]
	v_mfma_f32_16x16x32_bf16 v[128:131], v[156:159], v[164:167], v[128:131]
	v_mfma_f32_16x16x32_bf16 v[116:119], v[148:151], v[172:175], v[116:119]
	v_mfma_f32_16x16x32_bf16 v[112:115], v[156:159], v[172:175], v[112:115]
	v_mfma_f32_16x16x32_bf16 v[100:103], v[148:151], v[180:183], v[100:103]
	v_mfma_f32_16x16x32_bf16 v[96:99], v[156:159], v[180:183], v[96:99]
	v_mfma_f32_16x16x32_bf16 v[84:87], v[148:151], v[188:191], v[84:87]
	v_mfma_f32_16x16x32_bf16 v[80:83], v[156:159], v[188:191], v[80:83]
	s_barrier
	s_add_i32 s52, s78, s54
	s_mov_b32 m0, s52
	ds_read_b128 v[160:163], v243 offset:49152
	ds_read_b128 v[164:167], v243 offset:50176
	ds_read_b128 v[168:171], v243 offset:51200
	ds_read_b128 v[172:175], v243 offset:52224
	global_load_lds_dwordx4 v210, s[98:99]
	s_add_i32 m0, s52, 0x2000
	s_add_u32 s50, s50, 0x200080
	s_addc_u32 s51, s51, 0
	s_add_i32 s52, s79, s54
	global_load_lds_dwordx4 v214, s[98:99]
	s_mov_b32 m0, s52
	ds_read_b128 v[188:191], v243 offset:56320
	global_load_lds_dwordx4 v210, s[50:51]
	s_add_i32 m0, s52, 0x2000
	ds_read_b128 v[184:187], v243 offset:55296
	global_load_lds_dwordx4 v214, s[50:51]
	s_mov_b32 m0, s63
	ds_read_b128 v[180:183], v243 offset:54272
	global_load_lds_dwordx4 v208, s[100:101]
	s_mov_b32 m0, s68
	ds_read_b128 v[176:179], v243 offset:53248
	global_load_lds_dwordx4 v212, s[100:101]
	s_waitcnt vmcnt(8)
	s_waitcnt lgkmcnt(0)
	s_barrier
	s_waitcnt lgkmcnt(0)
	v_mfma_f32_16x16x32_bf16 v[76:79], v[56:59], v[160:163], v[76:79]
	v_mfma_f32_16x16x32_bf16 v[72:75], v[64:67], v[160:163], v[72:75]
	v_mfma_f32_16x16x32_bf16 v[44:47], v[56:59], v[168:171], v[44:47]
	v_mfma_f32_16x16x32_bf16 v[40:43], v[64:67], v[168:171], v[40:43]
	v_mfma_f32_16x16x32_bf16 v[28:31], v[56:59], v[176:179], v[28:31]
	v_mfma_f32_16x16x32_bf16 v[24:27], v[64:67], v[176:179], v[24:27]
	v_mfma_f32_16x16x32_bf16 v[12:15], v[56:59], v[184:187], v[12:15]
	v_mfma_f32_16x16x32_bf16 v[8:11], v[64:67], v[184:187], v[8:11]
	v_mfma_f32_16x16x32_bf16 v[76:79], v[60:63], v[164:167], v[76:79]
	v_mfma_f32_16x16x32_bf16 v[72:75], v[68:71], v[164:167], v[72:75]
	v_mfma_f32_16x16x32_bf16 v[44:47], v[60:63], v[172:175], v[44:47]
	v_mfma_f32_16x16x32_bf16 v[40:43], v[68:71], v[172:175], v[40:43]
	v_mfma_f32_16x16x32_bf16 v[28:31], v[60:63], v[180:183], v[28:31]
	v_mfma_f32_16x16x32_bf16 v[24:27], v[68:71], v[180:183], v[24:27]
	v_mfma_f32_16x16x32_bf16 v[12:15], v[60:63], v[188:191], v[12:15]
	v_mfma_f32_16x16x32_bf16 v[8:11], v[68:71], v[188:191], v[8:11]
	v_mfma_f32_16x16x32_bf16 v[52:55], v[144:147], v[160:163], v[52:55]
	v_mfma_f32_16x16x32_bf16 v[48:51], v[152:155], v[160:163], v[48:51]
	v_mfma_f32_16x16x32_bf16 v[36:39], v[144:147], v[168:171], v[36:39]
	v_mfma_f32_16x16x32_bf16 v[32:35], v[152:155], v[168:171], v[32:35]
	v_mfma_f32_16x16x32_bf16 v[20:23], v[144:147], v[176:179], v[20:23]
	v_mfma_f32_16x16x32_bf16 v[16:19], v[152:155], v[176:179], v[16:19]
	v_mfma_f32_16x16x32_bf16 v[4:7], v[144:147], v[184:187], v[4:7]
	v_mfma_f32_16x16x32_bf16 v[0:3], v[152:155], v[184:187], v[0:3]
	v_mfma_f32_16x16x32_bf16 v[52:55], v[148:151], v[164:167], v[52:55]
	v_mfma_f32_16x16x32_bf16 v[48:51], v[156:159], v[164:167], v[48:51]
	v_mfma_f32_16x16x32_bf16 v[36:39], v[148:151], v[172:175], v[36:39]
	v_mfma_f32_16x16x32_bf16 v[32:35], v[156:159], v[172:175], v[32:35]
	v_mfma_f32_16x16x32_bf16 v[20:23], v[148:151], v[180:183], v[20:23]
	v_mfma_f32_16x16x32_bf16 v[16:19], v[156:159], v[180:183], v[16:19]
	v_mfma_f32_16x16x32_bf16 v[4:7], v[148:151], v[188:191], v[4:7]
	v_mfma_f32_16x16x32_bf16 v[0:3], v[156:159], v[188:191], v[0:3]
	s_barrier
	s_add_i32 s77, s77, 2
	s_add_u32 s46, s46, 0x100
	s_addc_u32 s47, s47, 0
	s_add_u32 s75, s75, 0x100
	s_addc_u32 s76, s76, 0
	s_cmpk_gt_u32 s77, 0x7d
	s_cbranch_scc0 .LBB0_815
	s_and_b64 vcc, exec, s[14:15]
	s_cbranch_vccz .LBB0_818
	s_barrier
